# trailing half's post-epilogue barrier moved behind the scalar tile decode (just in front of the next unit's K-loop)
# baseline (speedup 1.0000x reference)
.LBB0_114:
	s_lshl_b32 s23, s23, 5
	s_mov_b64 s[74:75], 0x80
	s_and_b32 s33, s23, 0x60
	s_add_i32 m0, s17, 0x18000
	v_lshl_add_u64 v[6:7], v[6:7], 0, s[74:75]
	s_lshl_b32 s7, s6, 13
	s_lshl_b32 s52, s33, 7
	s_waitcnt vmcnt(2)
	s_barrier
	global_load_lds_dwordx4 v[6:7], off
	v_lshl_add_u64 v[4:5], v[4:5], 0, s[74:75]
	s_add_i32 m0, s17, 0x1a000
	s_add_i32 s23, s17, 0x8000
	s_add_i32 s24, s17, 0xa000
	global_load_lds_dwordx4 v[4:5], off
	v_lshl_add_u64 v[2:3], v[2:3], 0, s[74:75]
	s_mov_b32 m0, s23
	s_add_u32 s26, s90, 0x40080
	global_load_lds_dwordx4 v[2:3], off
	v_lshl_add_u64 v[0:1], v[0:1], 0, s[74:75]
	s_mov_b32 m0, s24
	s_addc_u32 s27, s91, 0
	global_load_lds_dwordx4 v[0:1], off
	s_add_i32 m0, s17, 0x1c000
	v_lshl_add_u64 v[0:1], s[26:27], 0, v[140:141]
	global_load_lds_dwordx4 v[0:1], off
	v_lshl_add_u64 v[0:1], s[26:27], 0, v[136:137]
	s_add_i32 m0, s17, 0x1e000
	v_mov_b32_e32 v145, 0
	global_load_lds_dwordx4 v[0:1], off
	v_and_b32_e32 v0, 15, v240
	v_bfe_u32 v1, v240, 4, 2
	v_lshl_or_b32 v174, s6, 6, v0
	s_lshl_b32 s6, s6, 8
	v_lshlrev_b32_e32 v144, 4, v1
	s_add_i32 s6, s6, 0
	v_lshl_or_b32 v2, v0, 6, v144
	v_lshlrev_b32_e32 v0, 2, v0
	s_add_i32 s6, s6, 0x20400
	v_and_b32_e32 v3, 32, v0
	v_add_u32_e32 v176, s6, v0
	v_lshlrev_b32_e32 v0, 8, v240
	v_lshl_or_b32 v177, v1, 3, s33
	v_and_b32_e32 v0, 0x38000, v0
	v_lshlrev_b32_e32 v1, 11, v15
	v_bitop3_b32 v2, v2, s7, v3 bitop3:0xde
	v_lshlrev_b32_e32 v3, 6, v240
	s_movk_i32 s7, 0x3c0
	v_or3_b32 v0, v13, v0, v1
	v_and_or_b32 v3, v3, s7, v144
	v_lshlrev_b32_e32 v4, 2, v240
	v_lshl_add_u64 v[146:147], s[70:71], 0, v[144:145]
	v_add_u32_e32 v144, v0, v14
	v_lshlrev_b32_e32 v0, 4, v12
	v_and_b32_e32 v4, 32, v4
	s_waitcnt vmcnt(6)
	s_cmpk_lt_u32 s25, 0x100
	v_and_b32_e32 v0, 0x78000, v0
	s_sext_i32_i8 s54, s76
	v_bitop3_b32 v175, s52, v3, v4 bitop3:0xf6
	s_cselect_b64 s[76:77], -1, 0
	v_or3_b32 v0, v13, v0, v1
	s_add_i32 s25, 0, 0x10000
	s_add_i32 s26, 0, 0x14000
	s_mov_b32 s55, 0
	v_add_u32_e32 v148, v0, v14
	v_mov_b32_e32 v149, v145
	v_mov_b64_e32 v[150:151], 0xb00
	v_mov_b64_e32 v[152:153], 0xaff
	v_add_u32_e32 v178, s25, v175
	v_add_u32_e32 v179, s26, v175
	v_add_u32_e32 v180, 0, v2
	v_mov_b32_e32 v181, 0x358637bd
	s_movk_i32 s27, 0x1600
	s_barrier
	s_mov_b32 s101, 0
	s_branch .LBB0_117

.LBB0_119:
	s_ashr_i32 s81, s80, 31
	s_lshl_b64 s[52:53], s[80:81], 19
	s_add_u32 s82, s12, s52
	s_addc_u32 s83, s13, s53
	s_and_b64 s[52:53], s[6:7], exec
	s_cselect_b32 s52, s83, s89
	s_cselect_b32 s53, s82, s88
	s_ashr_i32 s79, s78, 31
	s_lshl_b64 s[56:57], s[78:79], 19
	s_add_u32 s84, s14, s56
	s_addc_u32 s85, s15, s57
	s_and_b64 s[56:57], s[6:7], exec
	s_cselect_b32 s56, s85, s91
	s_cselect_b32 s57, s84, s90
	s_add_u32 s88, s88, 0x40080
	s_addc_u32 s89, s89, 0
	s_add_u32 s58, s90, 0x100
	v_mov_b32_e32 v0, 0
	s_addc_u32 s59, s91, 0
	s_mov_b32 s66, -2
	s_waitcnt lgkmcnt(0)
	s_cmp_eq_u32 s101, 0
	s_cbranch_scc1 .Lpb_0
	s_barrier
	s_mov_b32 s101, 0
.Lpb_0:
.LBB0_120:
	ds_read_b128 v[128:131], v178
	ds_read_b128 v[132:135], v178 offset:1024
	ds_read_b128 v[154:157], v178 offset:2048
	ds_read_b128 v[158:161], v178 offset:3072
	ds_read_b128 v[162:165], v179
	ds_read_b128 v[166:169], v179 offset:1024
	ds_read_b128 v[182:185], v179 offset:2048
	ds_read_b128 v[186:189], v179 offset:3072
	s_add_u32 s67, s88, 0xfffc0080
	s_addc_u32 s68, s89, -1
	s_cmp_eq_u32 s66, 12
	s_cselect_b32 s93, s52, s68
	s_cselect_b32 s92, s53, s67
	s_cselect_b32 s91, s56, s59
	s_cselect_b32 s90, s57, s58
	v_lshl_add_u64 v[170:171], s[88:89], 0, v[144:145]
	s_add_i32 m0, s17, 0xc000
	ds_read_b128 v[190:193], v180
	ds_read_b128 v[194:197], v180 offset:1024
	ds_read_b128 v[198:201], v180 offset:2048
	ds_read_b128 v[202:205], v180 offset:3072
	ds_read_b128 v[206:209], v180 offset:4096
	ds_read_b128 v[210:213], v180 offset:5120
	ds_read_b128 v[214:217], v180 offset:6144
	ds_read_b128 v[218:221], v180 offset:7168
	global_load_lds_dwordx4 v[170:171], off
	s_add_i32 m0, s17, 0xe000
	v_lshl_add_u64 v[170:171], s[88:89], 0, v[148:149]
	global_load_lds_dwordx4 v[170:171], off
	s_cmp_eq_u32 s66, -2
	s_waitcnt vmcnt(8) lgkmcnt(0)
	s_barrier
	s_setprio 1
	s_cbranch_scc1 .Lzv_0_0
	v_mfma_f32_16x16x32_bf16 v[124:127], v[128:131], v[190:193], v[124:127]
	v_mfma_f32_16x16x32_bf16 v[124:127], v[132:135], v[194:197], v[124:127]
	v_mfma_f32_16x16x32_bf16 v[116:119], v[154:157], v[190:193], v[116:119]
	v_mfma_f32_16x16x32_bf16 v[116:119], v[158:161], v[194:197], v[116:119]
	v_mfma_f32_16x16x32_bf16 v[108:111], v[128:131], v[198:201], v[108:111]
	v_mfma_f32_16x16x32_bf16 v[108:111], v[132:135], v[202:205], v[108:111]
	v_mfma_f32_16x16x32_bf16 v[100:103], v[154:157], v[198:201], v[100:103]
	v_mfma_f32_16x16x32_bf16 v[100:103], v[158:161], v[202:205], v[100:103]
	v_mfma_f32_16x16x32_bf16 v[92:95], v[128:131], v[206:209], v[92:95]
	v_mfma_f32_16x16x32_bf16 v[92:95], v[132:135], v[210:213], v[92:95]
	v_mfma_f32_16x16x32_bf16 v[84:87], v[154:157], v[206:209], v[84:87]
	v_mfma_f32_16x16x32_bf16 v[84:87], v[158:161], v[210:213], v[84:87]
	v_mfma_f32_16x16x32_bf16 v[76:79], v[128:131], v[214:217], v[76:79]
	v_mfma_f32_16x16x32_bf16 v[76:79], v[132:135], v[218:221], v[76:79]
	v_mfma_f32_16x16x32_bf16 v[68:71], v[154:157], v[214:217], v[68:71]
	v_mfma_f32_16x16x32_bf16 v[68:71], v[158:161], v[218:221], v[68:71]
	v_mfma_f32_16x16x32_bf16 v[120:123], v[162:165], v[190:193], v[120:123]
	v_mfma_f32_16x16x32_bf16 v[120:123], v[166:169], v[194:197], v[120:123]
	v_mfma_f32_16x16x32_bf16 v[112:115], v[182:185], v[190:193], v[112:115]
	v_mfma_f32_16x16x32_bf16 v[112:115], v[186:189], v[194:197], v[112:115]
	v_mfma_f32_16x16x32_bf16 v[104:107], v[162:165], v[198:201], v[104:107]
	v_mfma_f32_16x16x32_bf16 v[104:107], v[166:169], v[202:205], v[104:107]
	v_mfma_f32_16x16x32_bf16 v[96:99], v[182:185], v[198:201], v[96:99]
	v_mfma_f32_16x16x32_bf16 v[96:99], v[186:189], v[202:205], v[96:99]
	v_mfma_f32_16x16x32_bf16 v[88:91], v[162:165], v[206:209], v[88:91]
	v_mfma_f32_16x16x32_bf16 v[88:91], v[166:169], v[210:213], v[88:91]
	v_mfma_f32_16x16x32_bf16 v[80:83], v[182:185], v[206:209], v[80:83]
	v_mfma_f32_16x16x32_bf16 v[80:83], v[186:189], v[210:213], v[80:83]
	v_mfma_f32_16x16x32_bf16 v[72:75], v[162:165], v[214:217], v[72:75]
	v_mfma_f32_16x16x32_bf16 v[72:75], v[166:169], v[218:221], v[72:75]
	s_setprio 3
	s_barrier
	v_mfma_f32_16x16x32_bf16 v[64:67], v[182:185], v[214:217], v[64:67]
	v_mfma_f32_16x16x32_bf16 v[64:67], v[186:189], v[218:221], v[64:67]
	s_setprio 0

.LBB0_127:
	s_waitcnt lgkmcnt(0)
	v_mul_f32_e32 v130, 0xbfb8aa3b, v170
	v_mul_f32_e32 v131, v170, v170
	v_pk_mul_f32 v[168:169], v[126:127], v[130:131] op_sel_hi:[1,0]
	v_rcp_f32_e32 v134, v131
	v_pk_mul_f32 v[182:183], v[124:125], v[130:131] op_sel_hi:[1,0]
	v_exp_f32_e32 v168, v168
	v_exp_f32_e32 v169, v169
	v_pk_mul_f32 v[122:123], v[126:127], v[122:123]
	v_pk_mul_f32 v[126:127], v[116:117], v[130:131] op_sel_hi:[1,0]
	v_exp_f32_e32 v182, v182
	v_exp_f32_e32 v183, v183
	v_exp_f32_e32 v126, v126
	v_exp_f32_e32 v127, v127
	v_pk_mul_f32 v[120:121], v[124:125], v[120:121]
	v_pk_mul_f32 v[124:125], v[118:119], v[130:131] op_sel_hi:[1,0]
	v_pk_fma_f32 v[168:169], v[168:169], v[134:135], v[134:135] op_sel_hi:[1,0,0]
	v_exp_f32_e32 v124, v124
	v_exp_f32_e32 v125, v125
	v_pk_fma_f32 v[182:183], v[182:183], v[134:135], v[134:135] op_sel_hi:[1,0,0]
	v_rcp_f32_e32 v168, v168
	v_rcp_f32_e32 v169, v169
	v_pk_fma_f32 v[126:127], v[126:127], v[134:135], v[134:135] op_sel_hi:[1,0,0]
	v_rcp_f32_e32 v182, v182
	v_rcp_f32_e32 v183, v183
	v_rcp_f32_e32 v126, v126
	v_rcp_f32_e32 v127, v127
	v_pk_fma_f32 v[124:125], v[124:125], v[134:135], v[134:135] op_sel_hi:[1,0,0]
	v_pk_mul_f32 v[122:123], v[122:123], v[168:169]
	v_rcp_f32_e32 v124, v124
	v_rcp_f32_e32 v125, v125
	v_pk_mul_f32 v[112:113], v[116:117], v[112:113]
	v_pk_mul_f32 v[120:121], v[120:121], v[182:183]
	v_pk_mul_f32 v[112:113], v[112:113], v[126:127]
	v_cvt_pk_bf16_f32 v116, v120, v121
	v_cvt_pk_bf16_f32 v117, v122, v123
	v_mul_f32_e32 v122, 0xbfb8aa3b, v171
	v_mul_f32_e32 v123, v171, v171
	v_pk_mul_f32 v[114:115], v[118:119], v[114:115]
	v_cvt_pk_bf16_f32 v118, v112, v113
	v_mov_b64_e32 v[112:113], s[64:65]
	v_pk_mul_f32 v[126:127], v[110:111], v[122:123] op_sel_hi:[1,0]
	v_pk_mul_f32 v[130:131], v[108:109], v[122:123] op_sel_hi:[1,0]
	v_pk_mul_f32 v[106:107], v[110:111], v[106:107]
	v_pk_mul_f32 v[104:105], v[108:109], v[104:105]
	v_pk_mul_f32 v[108:109], v[102:103], v[122:123] op_sel_hi:[1,0]
	v_pk_mul_f32 v[110:111], v[100:101], v[122:123] op_sel_hi:[1,0]
	v_pk_mul_f32 v[114:115], v[114:115], v[124:125]
	v_mad_u64_u32 v[120:121], s[52:53], v164, s27, v[112:113]
	v_rcp_f32_e32 v124, v123
	v_exp_f32_e32 v110, v110
	v_exp_f32_e32 v108, v108
	v_exp_f32_e32 v109, v109
	v_exp_f32_e32 v111, v111
	v_lshl_or_b32 v184, s54, 7, v177
	v_cvt_pk_bf16_f32 v119, v114, v115
	v_exp_f32_e32 v130, v130
	v_exp_f32_e32 v126, v126
	v_exp_f32_e32 v127, v127
	v_exp_f32_e32 v131, v131
	v_ashrrev_i32_e32 v185, 31, v184
	v_lshlrev_b64 v[114:115], 1, v[184:185]
	v_lshl_add_u64 v[120:121], v[120:121], 0, v[114:115]
	v_pk_fma_f32 v[108:109], v[108:109], v[124:125], v[124:125] op_sel_hi:[1,0,0]
	v_pk_fma_f32 v[110:111], v[110:111], v[124:125], v[124:125] op_sel_hi:[1,0,0]
	global_store_dwordx4 v[120:121], v[116:119], off
	v_rcp_f32_e32 v110, v110
	v_rcp_f32_e32 v108, v108
	v_pk_fma_f32 v[116:117], v[126:127], v[124:125], v[124:125] op_sel_hi:[1,0,0]
	v_pk_fma_f32 v[118:119], v[130:131], v[124:125], v[124:125] op_sel_hi:[1,0,0]
	v_rcp_f32_e32 v109, v109
	v_rcp_f32_e32 v111, v111
	v_rcp_f32_e32 v118, v118
	v_rcp_f32_e32 v119, v119
	v_rcp_f32_e32 v116, v116
	v_rcp_f32_e32 v117, v117
	v_pk_mul_f32 v[98:99], v[102:103], v[98:99]
	v_pk_mul_f32 v[96:97], v[100:101], v[96:97]
	v_pk_mul_f32 v[100:101], v[98:99], v[108:109]
	v_pk_mul_f32 v[98:99], v[96:97], v[110:111]
	v_pk_mul_f32 v[106:107], v[106:107], v[116:117]
	v_pk_mul_f32 v[104:105], v[104:105], v[118:119]
	v_pk_mul_f32 v[90:91], v[94:95], v[90:91]
	v_cvt_pk_bf16_f32 v96, v104, v105
	v_cvt_pk_bf16_f32 v97, v106, v107
	v_cvt_pk_bf16_f32 v98, v98, v99
	v_cvt_pk_bf16_f32 v99, v100, v101
	v_mad_u64_u32 v[100:101], s[52:53], v160, s27, v[112:113]
	v_mul_f32_e32 v102, 0xbfb8aa3b, v166
	v_mul_f32_e32 v103, v166, v166
	v_pk_mul_f32 v[106:107], v[94:95], v[102:103] op_sel_hi:[1,0]
	v_pk_mul_f32 v[108:109], v[92:93], v[102:103] op_sel_hi:[1,0]
	v_pk_mul_f32 v[88:89], v[92:93], v[88:89]
	v_pk_mul_f32 v[92:93], v[86:87], v[102:103] op_sel_hi:[1,0]
	v_pk_mul_f32 v[94:95], v[84:85], v[102:103] op_sel_hi:[1,0]
	v_rcp_f32_e32 v104, v103
	v_exp_f32_e32 v94, v94
	v_exp_f32_e32 v92, v92
	v_exp_f32_e32 v93, v93
	v_exp_f32_e32 v95, v95
	v_exp_f32_e32 v108, v108
	v_exp_f32_e32 v106, v106
	v_exp_f32_e32 v107, v107
	v_exp_f32_e32 v109, v109
	v_lshl_add_u64 v[100:101], v[100:101], 0, v[114:115]
	v_pk_fma_f32 v[92:93], v[92:93], v[104:105], v[104:105] op_sel_hi:[1,0,0]
	v_pk_fma_f32 v[94:95], v[94:95], v[104:105], v[104:105] op_sel_hi:[1,0,0]
	global_store_dwordx4 v[100:101], v[96:99], off
	v_rcp_f32_e32 v94, v94
	v_rcp_f32_e32 v92, v92
	v_pk_fma_f32 v[96:97], v[106:107], v[104:105], v[104:105] op_sel_hi:[1,0,0]
	v_pk_fma_f32 v[98:99], v[108:109], v[104:105], v[104:105] op_sel_hi:[1,0,0]
	v_rcp_f32_e32 v93, v93
	v_rcp_f32_e32 v95, v95
	v_rcp_f32_e32 v98, v98
	v_rcp_f32_e32 v99, v99
	v_rcp_f32_e32 v96, v96
	v_rcp_f32_e32 v97, v97
	v_pk_mul_f32 v[82:83], v[86:87], v[82:83]
	v_pk_mul_f32 v[80:81], v[84:85], v[80:81]
	v_pk_mul_f32 v[84:85], v[82:83], v[92:93]
	v_pk_mul_f32 v[82:83], v[80:81], v[94:95]
	v_pk_mul_f32 v[90:91], v[90:91], v[96:97]
	v_pk_mul_f32 v[88:89], v[88:89], v[98:99]
	v_pk_mul_f32 v[74:75], v[78:79], v[74:75]
	v_cvt_pk_bf16_f32 v80, v88, v89
	v_cvt_pk_bf16_f32 v81, v90, v91
	v_cvt_pk_bf16_f32 v82, v82, v83
	v_cvt_pk_bf16_f32 v83, v84, v85
	v_mad_u64_u32 v[84:85], s[52:53], v158, s27, v[112:113]
	v_mul_f32_e32 v86, 0xbfb8aa3b, v167
	v_mul_f32_e32 v87, v167, v167
	v_pk_mul_f32 v[90:91], v[78:79], v[86:87] op_sel_hi:[1,0]
	v_pk_mul_f32 v[92:93], v[76:77], v[86:87] op_sel_hi:[1,0]
	v_pk_mul_f32 v[72:73], v[76:77], v[72:73]
	v_pk_mul_f32 v[76:77], v[70:71], v[86:87] op_sel_hi:[1,0]
	v_pk_mul_f32 v[78:79], v[68:69], v[86:87] op_sel_hi:[1,0]
	v_rcp_f32_e32 v88, v87
	v_exp_f32_e32 v78, v78
	v_exp_f32_e32 v76, v76
	v_exp_f32_e32 v77, v77
	v_exp_f32_e32 v79, v79
	v_exp_f32_e32 v92, v92
	v_exp_f32_e32 v90, v90
	v_exp_f32_e32 v91, v91
	v_exp_f32_e32 v93, v93
	v_lshl_add_u64 v[84:85], v[84:85], 0, v[114:115]
	v_pk_fma_f32 v[76:77], v[76:77], v[88:89], v[88:89] op_sel_hi:[1,0,0]
	v_pk_fma_f32 v[78:79], v[78:79], v[88:89], v[88:89] op_sel_hi:[1,0,0]
	global_store_dwordx4 v[84:85], v[80:83], off
	v_rcp_f32_e32 v78, v78
	v_rcp_f32_e32 v76, v76
	v_pk_fma_f32 v[80:81], v[90:91], v[88:89], v[88:89] op_sel_hi:[1,0,0]
	v_pk_fma_f32 v[82:83], v[92:93], v[88:89], v[88:89] op_sel_hi:[1,0,0]
	v_rcp_f32_e32 v77, v77
	v_rcp_f32_e32 v79, v79
	v_rcp_f32_e32 v82, v82
	v_rcp_f32_e32 v83, v83
	v_rcp_f32_e32 v80, v80
	v_rcp_f32_e32 v81, v81
	v_pk_mul_f32 v[66:67], v[70:71], v[66:67]
	v_pk_mul_f32 v[64:65], v[68:69], v[64:65]
	v_pk_mul_f32 v[68:69], v[66:67], v[76:77]
	v_pk_mul_f32 v[66:67], v[64:65], v[78:79]
	v_pk_mul_f32 v[74:75], v[74:75], v[80:81]
	v_pk_mul_f32 v[72:73], v[72:73], v[82:83]
	v_pk_mul_f32 v[58:59], v[62:63], v[58:59]
	v_cvt_pk_bf16_f32 v64, v72, v73
	v_cvt_pk_bf16_f32 v65, v74, v75
	v_cvt_pk_bf16_f32 v66, v66, v67
	v_cvt_pk_bf16_f32 v67, v68, v69
	v_mad_u64_u32 v[68:69], s[52:53], v156, s27, v[112:113]
	v_mul_f32_e32 v70, 0xbfb8aa3b, v162
	v_mul_f32_e32 v71, v162, v162
	v_pk_mul_f32 v[74:75], v[62:63], v[70:71] op_sel_hi:[1,0]
	v_pk_mul_f32 v[76:77], v[60:61], v[70:71] op_sel_hi:[1,0]
	v_pk_mul_f32 v[56:57], v[60:61], v[56:57]
	v_pk_mul_f32 v[60:61], v[54:55], v[70:71] op_sel_hi:[1,0]
	v_pk_mul_f32 v[62:63], v[52:53], v[70:71] op_sel_hi:[1,0]
	v_rcp_f32_e32 v72, v71
	v_exp_f32_e32 v62, v62
	v_exp_f32_e32 v60, v60
	v_exp_f32_e32 v61, v61
	v_exp_f32_e32 v63, v63
	v_exp_f32_e32 v76, v76
	v_exp_f32_e32 v74, v74
	v_exp_f32_e32 v75, v75
	v_exp_f32_e32 v77, v77
	v_lshl_add_u64 v[68:69], v[68:69], 0, v[114:115]
	v_pk_fma_f32 v[60:61], v[60:61], v[72:73], v[72:73] op_sel_hi:[1,0,0]
	v_pk_fma_f32 v[62:63], v[62:63], v[72:73], v[72:73] op_sel_hi:[1,0,0]
	global_store_dwordx4 v[68:69], v[64:67], off
	v_rcp_f32_e32 v62, v62
	v_rcp_f32_e32 v60, v60
	v_pk_fma_f32 v[64:65], v[74:75], v[72:73], v[72:73] op_sel_hi:[1,0,0]
	v_pk_fma_f32 v[66:67], v[76:77], v[72:73], v[72:73] op_sel_hi:[1,0,0]
	v_rcp_f32_e32 v61, v61
	v_rcp_f32_e32 v63, v63
	v_rcp_f32_e32 v66, v66
	v_rcp_f32_e32 v67, v67
	v_rcp_f32_e32 v64, v64
	v_rcp_f32_e32 v65, v65
	v_pk_mul_f32 v[50:51], v[54:55], v[50:51]
	v_pk_mul_f32 v[48:49], v[52:53], v[48:49]
	v_pk_mul_f32 v[52:53], v[50:51], v[60:61]
	v_pk_mul_f32 v[50:51], v[48:49], v[62:63]
	v_pk_mul_f32 v[58:59], v[58:59], v[64:65]
	v_pk_mul_f32 v[56:57], v[56:57], v[66:67]
	v_pk_mul_f32 v[42:43], v[46:47], v[42:43]
	v_cvt_pk_bf16_f32 v48, v56, v57
	v_cvt_pk_bf16_f32 v49, v58, v59
	v_cvt_pk_bf16_f32 v50, v50, v51
	v_cvt_pk_bf16_f32 v51, v52, v53
	v_mad_u64_u32 v[52:53], s[52:53], v128, s27, v[112:113]
	v_mov_b32_e32 v54, v53
	v_mad_u64_u32 v[54:55], s[52:53], v129, s27, v[54:55]
	v_mov_b32_e32 v53, v54
	v_mul_f32_e32 v54, 0xbfb8aa3b, v163
	v_mul_f32_e32 v55, v163, v163
	v_pk_mul_f32 v[58:59], v[46:47], v[54:55] op_sel_hi:[1,0]
	v_pk_mul_f32 v[60:61], v[44:45], v[54:55] op_sel_hi:[1,0]
	v_pk_mul_f32 v[40:41], v[44:45], v[40:41]
	v_pk_mul_f32 v[44:45], v[38:39], v[54:55] op_sel_hi:[1,0]
	v_pk_mul_f32 v[46:47], v[36:37], v[54:55] op_sel_hi:[1,0]
	v_rcp_f32_e32 v56, v55
	v_exp_f32_e32 v46, v46
	v_exp_f32_e32 v44, v44
	v_exp_f32_e32 v45, v45
	v_exp_f32_e32 v47, v47
	v_exp_f32_e32 v60, v60
	v_exp_f32_e32 v58, v58
	v_exp_f32_e32 v59, v59
	v_exp_f32_e32 v61, v61
	v_lshl_add_u64 v[52:53], v[52:53], 0, v[114:115]
	v_pk_fma_f32 v[44:45], v[44:45], v[56:57], v[56:57] op_sel_hi:[1,0,0]
	v_pk_fma_f32 v[46:47], v[46:47], v[56:57], v[56:57] op_sel_hi:[1,0,0]
	global_store_dwordx4 v[52:53], v[48:51], off
	v_rcp_f32_e32 v46, v46
	v_rcp_f32_e32 v44, v44
	v_pk_fma_f32 v[48:49], v[58:59], v[56:57], v[56:57] op_sel_hi:[1,0,0]
	v_pk_fma_f32 v[50:51], v[60:61], v[56:57], v[56:57] op_sel_hi:[1,0,0]
	v_rcp_f32_e32 v45, v45
	v_rcp_f32_e32 v47, v47
	v_rcp_f32_e32 v50, v50
	v_rcp_f32_e32 v51, v51
	v_rcp_f32_e32 v48, v48
	v_rcp_f32_e32 v49, v49
	v_pk_mul_f32 v[34:35], v[38:39], v[34:35]
	v_pk_mul_f32 v[32:33], v[36:37], v[32:33]
	v_pk_mul_f32 v[36:37], v[34:35], v[44:45]
	v_pk_mul_f32 v[34:35], v[32:33], v[46:47]
	v_add_u32_e32 v38, 16, v154
	v_pk_mul_f32 v[42:43], v[42:43], v[48:49]
	v_pk_mul_f32 v[40:41], v[40:41], v[50:51]
	v_mul_f32_e32 v39, v132, v132
	v_cvt_pk_bf16_f32 v32, v40, v41
	v_cvt_pk_bf16_f32 v33, v42, v43
	v_cvt_pk_bf16_f32 v34, v34, v35
	v_cvt_pk_bf16_f32 v35, v36, v37
	v_mad_i64_i32 v[36:37], s[52:53], v38, s27, v[112:113]
	v_mul_f32_e32 v38, 0xbfb8aa3b, v132
	v_pk_mul_f32 v[42:43], v[30:31], v[38:39] op_sel_hi:[1,0]
	v_pk_mul_f32 v[44:45], v[28:29], v[38:39] op_sel_hi:[1,0]
	v_pk_mul_f32 v[26:27], v[30:31], v[26:27]
	v_pk_mul_f32 v[24:25], v[28:29], v[24:25]
	v_pk_mul_f32 v[28:29], v[22:23], v[38:39] op_sel_hi:[1,0]
	v_pk_mul_f32 v[30:31], v[20:21], v[38:39] op_sel_hi:[1,0]
	v_rcp_f32_e32 v40, v39
	v_exp_f32_e32 v30, v30
	v_exp_f32_e32 v28, v28
	v_exp_f32_e32 v29, v29
	v_exp_f32_e32 v31, v31
	v_exp_f32_e32 v44, v44
	v_exp_f32_e32 v42, v42
	v_exp_f32_e32 v43, v43
	v_exp_f32_e32 v45, v45
	v_lshl_add_u64 v[36:37], v[36:37], 0, v[114:115]
	v_pk_fma_f32 v[28:29], v[28:29], v[40:41], v[40:41] op_sel_hi:[1,0,0]
	v_pk_fma_f32 v[30:31], v[30:31], v[40:41], v[40:41] op_sel_hi:[1,0,0]
	global_store_dwordx4 v[36:37], v[32:35], off
	v_rcp_f32_e32 v30, v30
	v_rcp_f32_e32 v28, v28
	v_pk_fma_f32 v[32:33], v[42:43], v[40:41], v[40:41] op_sel_hi:[1,0,0]
	v_pk_fma_f32 v[34:35], v[44:45], v[40:41], v[40:41] op_sel_hi:[1,0,0]
	v_rcp_f32_e32 v29, v29
	v_rcp_f32_e32 v31, v31
	v_rcp_f32_e32 v34, v34
	v_rcp_f32_e32 v35, v35
	v_rcp_f32_e32 v32, v32
	v_rcp_f32_e32 v33, v33
	v_pk_mul_f32 v[18:19], v[22:23], v[18:19]
	v_pk_mul_f32 v[16:17], v[20:21], v[16:17]
	v_pk_mul_f32 v[20:21], v[18:19], v[28:29]
	v_pk_mul_f32 v[18:19], v[16:17], v[30:31]
	v_add_u32_e32 v22, 32, v154
	v_pk_mul_f32 v[26:27], v[26:27], v[32:33]
	v_pk_mul_f32 v[24:25], v[24:25], v[34:35]
	v_mul_f32_e32 v23, v133, v133
	v_cvt_pk_bf16_f32 v16, v24, v25
	v_cvt_pk_bf16_f32 v17, v26, v27
	v_cvt_pk_bf16_f32 v18, v18, v19
	v_cvt_pk_bf16_f32 v19, v20, v21
	v_mad_i64_i32 v[20:21], s[52:53], v22, s27, v[112:113]
	v_mul_f32_e32 v22, 0xbfb8aa3b, v133
	v_pk_mul_f32 v[26:27], v[14:15], v[22:23] op_sel_hi:[1,0]
	v_pk_mul_f32 v[28:29], v[12:13], v[22:23] op_sel_hi:[1,0]
	v_pk_mul_f32 v[10:11], v[14:15], v[10:11]
	v_pk_mul_f32 v[8:9], v[12:13], v[8:9]
	v_pk_mul_f32 v[12:13], v[6:7], v[22:23] op_sel_hi:[1,0]
	v_pk_mul_f32 v[14:15], v[4:5], v[22:23] op_sel_hi:[1,0]
	v_rcp_f32_e32 v24, v23
	v_exp_f32_e32 v14, v14
	v_exp_f32_e32 v12, v12
	v_exp_f32_e32 v13, v13
	v_exp_f32_e32 v15, v15
	v_exp_f32_e32 v28, v28
	v_exp_f32_e32 v26, v26
	v_exp_f32_e32 v27, v27
	v_exp_f32_e32 v29, v29
	v_lshl_add_u64 v[20:21], v[20:21], 0, v[114:115]
	v_pk_fma_f32 v[12:13], v[12:13], v[24:25], v[24:25] op_sel_hi:[1,0,0]
	v_pk_fma_f32 v[14:15], v[14:15], v[24:25], v[24:25] op_sel_hi:[1,0,0]
	global_store_dwordx4 v[20:21], v[16:19], off
	v_rcp_f32_e32 v14, v14
	v_rcp_f32_e32 v12, v12
	v_pk_fma_f32 v[16:17], v[26:27], v[24:25], v[24:25] op_sel_hi:[1,0,0]
	v_pk_fma_f32 v[18:19], v[28:29], v[24:25], v[24:25] op_sel_hi:[1,0,0]
	v_rcp_f32_e32 v13, v13
	v_rcp_f32_e32 v15, v15
	v_rcp_f32_e32 v18, v18
	v_rcp_f32_e32 v19, v19
	v_rcp_f32_e32 v16, v16
	v_rcp_f32_e32 v17, v17
	v_pk_mul_f32 v[2:3], v[6:7], v[2:3]
	v_pk_mul_f32 v[0:1], v[4:5], v[0:1]
	v_pk_mul_f32 v[4:5], v[2:3], v[12:13]
	v_pk_mul_f32 v[2:3], v[0:1], v[14:15]
	v_add_u32_e32 v6, 48, v154
	v_pk_mul_f32 v[10:11], v[10:11], v[16:17]
	v_pk_mul_f32 v[8:9], v[8:9], v[18:19]
	s_andn2_b64 vcc, exec, s[6:7]
	v_cvt_pk_bf16_f32 v0, v8, v9
	v_cvt_pk_bf16_f32 v1, v10, v11
	v_cvt_pk_bf16_f32 v2, v2, v3
	v_cvt_pk_bf16_f32 v3, v4, v5
	v_mad_i64_i32 v[4:5], s[52:53], v6, s27, v[112:113]
	v_lshl_add_u64 v[4:5], v[4:5], 0, v[114:115]
	s_mov_b64 s[6:7], -1
	global_store_dwordx4 v[4:5], v[0:3], off
	s_cbranch_vccnz .LBB0_116
	s_andn2_b64 vcc, exec, s[10:11]
	s_cbranch_vccnz .LBB0_115
	s_mov_b32 s101, 1
	s_branch .LBB0_115

.LBB0_258:
	v_bfe_u32 v12, v240, 4, 2
	v_and_b32_e32 v13, 15, v240
	v_lshlrev_b32_e32 v15, 4, v12
	v_lshlrev_b32_e32 v16, 2, v240
	s_and_b32 s20, s6, 3
	v_lshl_or_b32 v242, s7, 6, v13
	v_lshl_or_b32 v13, v13, 6, v15
	s_lshl_b32 s6, s7, 13
	v_and_b32_e32 v16, 32, v16
	s_mov_b64 s[80:81], 0x80
	v_bitop3_b32 v13, v13, s6, v16 bitop3:0xde
	v_lshlrev_b32_e32 v17, 6, v240
	s_movk_i32 s6, 0x3c0
	s_add_i32 m0, s16, 0x18000
	v_lshl_add_u64 v[6:7], v[6:7], 0, s[80:81]
	v_and_or_b32 v15, v17, s6, v15
	s_lshl_b32 s6, s20, 12
	s_waitcnt vmcnt(2)
	s_barrier
	global_load_lds_dwordx4 v[6:7], off
	v_lshl_add_u64 v[4:5], v[4:5], 0, s[80:81]
	s_add_i32 m0, s16, 0x1a000
	s_add_i32 s21, s16, 0x8000
	s_add_i32 s22, s16, 0xa000
	v_bitop3_b32 v243, s6, v15, v16 bitop3:0xf6
	global_load_lds_dwordx4 v[4:5], off
	v_lshl_add_u64 v[0:1], v[0:1], 0, s[80:81]
	s_mov_b32 m0, s21
	s_add_u32 s6, s88, 0xb0080
	global_load_lds_dwordx4 v[0:1], off
	v_lshl_add_u64 v[0:1], v[2:3], 0, s[80:81]
	s_mov_b32 m0, s22
	s_addc_u32 s7, s89, 0
	global_load_lds_dwordx4 v[0:1], off
	s_add_i32 m0, s16, 0x1c000
	v_lshl_add_u64 v[0:1], s[6:7], 0, v[194:195]
	global_load_lds_dwordx4 v[0:1], off
	v_lshl_add_u64 v[0:1], s[6:7], 0, v[198:199]
	s_add_i32 m0, s16, 0x1e000
	s_cmpk_lt_u32 s10, 0x100
	global_load_lds_dwordx4 v[0:1], off
	v_add_u16_e32 v0, v8, v9
	s_waitcnt vmcnt(6)
	v_lshrrev_b16_e32 v0, 1, v0
	s_waitcnt lgkmcnt(0)
	v_lshlrev_b32_e32 v14, 3, v12
	s_cselect_b64 s[82:83], -1, 0
	v_add_lshl_u32 v200, v10, v0, 1
	v_add_lshl_u32 v202, v11, v0, 1
	s_add_i32 s26, 0, 0x10000
	s_add_i32 s27, 0, 0x14000
	v_mbcnt_lo_u32_b32 v0, -1, 0
	v_lshl_or_b32 v244, s20, 5, v14
	v_cmp_eq_u32_e64 s[6:7], 0, v12
	s_ashr_i32 s23, s34, 31
	s_mov_b32 s24, s34
	s_ashr_i32 s25, s2, 31
	v_mov_b32_e32 v201, v195
	v_mov_b32_e32 v203, v195
	v_add_u32_e32 v245, s26, v243
	v_add_u32_e32 v246, s27, v243
	v_add_u32_e32 v247, 0, v13
	v_mbcnt_hi_u32_b32 v248, -1, v0
	s_mov_b32 s33, 0
	s_barrier
	s_mov_b32 s101, 0
	s_branch .LBB0_261

.LBB0_271:
	s_add_u32 s86, s86, 0xb0080
	s_addc_u32 s87, s87, 0
	s_add_u32 s56, s88, 0x100
	v_mov_b32_e32 v0, 0
	s_addc_u32 s57, s89, 0
	s_mov_b32 s58, -2
	s_cmp_eq_u32 s101, 0
	s_cbranch_scc1 .Lpb_1
	s_barrier
	s_mov_b32 s101, 0
.Lpb_1:
.LBB0_272:
	ds_read_b128 v[120:123], v245
	ds_read_b128 v[124:127], v245 offset:1024
	ds_read_b128 v[128:131], v245 offset:2048
	ds_read_b128 v[132:135], v245 offset:3072
	ds_read_b128 v[144:147], v246
	ds_read_b128 v[148:151], v246 offset:1024
	ds_read_b128 v[152:155], v246 offset:2048
	ds_read_b128 v[156:159], v246 offset:3072
	s_add_u32 s59, s86, 0xfff50080
	s_addc_u32 s66, s87, -1
	s_cmp_eq_u32 s58, 40
	s_cselect_b32 s91, s11, s66
	s_cselect_b32 s90, s10, s59
	s_cselect_b32 s89, s85, s57
	s_cselect_b32 s88, s84, s56
	v_lshl_add_u64 v[204:205], s[86:87], 0, v[200:201]
	s_add_i32 m0, s16, 0xc000
	ds_read_b128 v[160:163], v247
	ds_read_b128 v[164:167], v247 offset:1024
	ds_read_b128 v[168:171], v247 offset:2048
	ds_read_b128 v[172:175], v247 offset:3072
	ds_read_b128 v[176:179], v247 offset:4096
	ds_read_b128 v[180:183], v247 offset:5120
	ds_read_b128 v[184:187], v247 offset:6144
	ds_read_b128 v[188:191], v247 offset:7168
	global_load_lds_dwordx4 v[204:205], off
	s_add_i32 m0, s16, 0xe000
	v_lshl_add_u64 v[204:205], s[86:87], 0, v[202:203]
	global_load_lds_dwordx4 v[204:205], off
	s_cmp_eq_u32 s58, -2
	s_waitcnt vmcnt(8) lgkmcnt(0)
	s_barrier
	s_setprio 1
	s_cbranch_scc1 .Lzv_1_0
	v_mfma_f32_16x16x32_bf16 v[140:143], v[120:123], v[160:163], v[140:143]
	v_mfma_f32_16x16x32_bf16 v[140:143], v[124:127], v[164:167], v[140:143]
	v_mfma_f32_16x16x32_bf16 v[136:139], v[128:131], v[160:163], v[136:139]
	v_mfma_f32_16x16x32_bf16 v[136:139], v[132:135], v[164:167], v[136:139]
	v_mfma_f32_16x16x32_bf16 v[108:111], v[120:123], v[168:171], v[108:111]
	v_mfma_f32_16x16x32_bf16 v[108:111], v[124:127], v[172:175], v[108:111]
	v_mfma_f32_16x16x32_bf16 v[104:107], v[128:131], v[168:171], v[104:107]
	v_mfma_f32_16x16x32_bf16 v[104:107], v[132:135], v[172:175], v[104:107]
	v_mfma_f32_16x16x32_bf16 v[92:95], v[120:123], v[176:179], v[92:95]
	v_mfma_f32_16x16x32_bf16 v[92:95], v[124:127], v[180:183], v[92:95]
	v_mfma_f32_16x16x32_bf16 v[88:91], v[128:131], v[176:179], v[88:91]
	v_mfma_f32_16x16x32_bf16 v[88:91], v[132:135], v[180:183], v[88:91]
	v_mfma_f32_16x16x32_bf16 v[76:79], v[120:123], v[184:187], v[76:79]
	v_mfma_f32_16x16x32_bf16 v[76:79], v[124:127], v[188:191], v[76:79]
	v_mfma_f32_16x16x32_bf16 v[72:75], v[128:131], v[184:187], v[72:75]
	v_mfma_f32_16x16x32_bf16 v[72:75], v[132:135], v[188:191], v[72:75]
	v_mfma_f32_16x16x32_bf16 v[116:119], v[144:147], v[160:163], v[116:119]
	v_mfma_f32_16x16x32_bf16 v[116:119], v[148:151], v[164:167], v[116:119]
	v_mfma_f32_16x16x32_bf16 v[112:115], v[152:155], v[160:163], v[112:115]
	v_mfma_f32_16x16x32_bf16 v[112:115], v[156:159], v[164:167], v[112:115]
	v_mfma_f32_16x16x32_bf16 v[100:103], v[144:147], v[168:171], v[100:103]
	v_mfma_f32_16x16x32_bf16 v[100:103], v[148:151], v[172:175], v[100:103]
	v_mfma_f32_16x16x32_bf16 v[96:99], v[152:155], v[168:171], v[96:99]
	v_mfma_f32_16x16x32_bf16 v[96:99], v[156:159], v[172:175], v[96:99]
	v_mfma_f32_16x16x32_bf16 v[84:87], v[144:147], v[176:179], v[84:87]
	v_mfma_f32_16x16x32_bf16 v[84:87], v[148:151], v[180:183], v[84:87]
	v_mfma_f32_16x16x32_bf16 v[80:83], v[152:155], v[176:179], v[80:83]
	v_mfma_f32_16x16x32_bf16 v[80:83], v[156:159], v[180:183], v[80:83]
	v_mfma_f32_16x16x32_bf16 v[68:71], v[144:147], v[184:187], v[68:71]
	v_mfma_f32_16x16x32_bf16 v[68:71], v[148:151], v[188:191], v[68:71]
	s_setprio 3
	s_barrier
	v_mfma_f32_16x16x32_bf16 v[64:67], v[152:155], v[184:187], v[64:67]
	v_mfma_f32_16x16x32_bf16 v[64:67], v[156:159], v[188:191], v[64:67]
	s_setprio 0

.LBB0_291:
	s_or_b64 exec, exec, s[52:53]
	s_and_b64 vcc, exec, s[8:9]
	s_mov_b64 s[8:9], -1
	s_cbranch_vccnz .LBB0_260
	s_andn2_b64 vcc, exec, s[78:79]
	s_cbranch_vccnz .LBB0_259
	s_mov_b32 s101, 1
	s_branch .LBB0_259

.LBB0_423:
	s_mov_b64 s[80:81], 0x80
	s_lshl_b32 s9, s8, 8
	s_and_b32 s29, s16, 3
	s_add_i32 m0, s58, 0x18000
	v_lshl_add_u64 v[6:7], v[6:7], 0, s[80:81]
	s_add_i32 s10, s9, 0
	s_lshl_b32 s73, s8, 6
	s_lshl_b32 s11, s8, 13
	s_lshl_b32 s17, s29, 12
	s_waitcnt vmcnt(2)
	s_barrier
	global_load_lds_dwordx4 v[6:7], off
	v_lshl_add_u64 v[4:5], v[4:5], 0, s[80:81]
	s_add_i32 m0, s58, 0x1a000
	s_add_i32 s93, s58, 0x8000
	s_add_i32 s69, s58, 0xa000
	global_load_lds_dwordx4 v[4:5], off
	v_lshl_add_u64 v[2:3], v[2:3], 0, s[80:81]
	s_mov_b32 m0, s93
	s_add_u32 s8, s6, 0x40080
	global_load_lds_dwordx4 v[2:3], off
	v_lshl_add_u64 v[0:1], v[0:1], 0, s[80:81]
	s_mov_b32 m0, s69
	s_addc_u32 s9, s7, 0
	global_load_lds_dwordx4 v[0:1], off
	s_add_i32 m0, s58, 0x1c000
	v_lshl_add_u64 v[0:1], s[8:9], 0, v[142:143]
	global_load_lds_dwordx4 v[0:1], off
	v_lshl_add_u64 v[0:1], s[8:9], 0, v[146:147]
	s_add_i32 m0, s58, 0x1e000
	s_movk_i32 s8, 0x3c0
	global_load_lds_dwordx4 v[0:1], off
	v_lshrrev_b32_e32 v0, 4, v240
	v_bfe_u32 v1, v240, 4, 2
	v_lshlrev_b32_e32 v148, 3, v1
	v_lshlrev_b32_e32 v150, 4, v1
	v_lshlrev_b32_e32 v1, 6, v240
	v_lshlrev_b32_e32 v2, 2, v240
	v_bitop3_b32 v0, s16, v0, 3 bitop3:0xa8
	v_and_or_b32 v1, v1, s8, v150
	v_and_b32_e32 v2, 32, v2
	v_cmp_eq_u32_e64 s[8:9], 0, v0
	v_lshlrev_b32_e32 v0, 8, v240
	v_bitop3_b32 v200, s17, v1, v2 bitop3:0xf6
	v_and_b32_e32 v0, 0x38000, v0
	v_lshlrev_b32_e32 v1, 11, v14
	v_and_b32_e32 v199, 15, v240
	v_or3_b32 v0, v12, v0, v1
	v_lshlrev_b32_e32 v3, 2, v199
	s_add_i32 s10, s10, 0x20400
	v_add_u32_e32 v156, v0, v13
	v_lshlrev_b32_e32 v0, 4, v15
	v_lshl_or_b32 v4, v199, 6, v150
	v_and_b32_e32 v5, 32, v3
	s_waitcnt vmcnt(6)
	s_cmpk_lt_u32 s15, 0x100
	v_and_b32_e32 v0, 0x78000, v0
	v_mov_b32_e32 v151, 0
	v_bitop3_b32 v4, v4, s11, v5 bitop3:0xde
	v_lshl_or_b32 v154, s29, 5, v148
	s_cselect_b64 s[82:83], -1, 0
	v_or3_b32 v0, v12, v0, v1
	s_add_i32 s76, 0, 0x10000
	s_add_i32 s77, 0, 0x14000
	s_mov_b32 s14, 0
	v_lshl_add_u64 v[152:153], s[70:71], 0, v[150:151]
	v_add_u32_e32 v201, s10, v3
	v_or_b32_e32 v202, 0xfffff800, v154
	v_writelane_b32 v254, s8, 57
	v_mov_b32_e32 v157, v151
	v_add_u32_e32 v158, v0, v13
	v_mov_b32_e32 v159, v151
	v_mov_b64_e32 v[160:161], 0x500
	v_mov_b64_e32 v[162:163], 0x4ff
	v_add_u32_e32 v203, s76, v200
	v_add_u32_e32 v204, s77, v200
	v_add_u32_e32 v205, 0, v4
	v_mov_b32_e32 v206, 0x358637bd
	s_mov_b32 s87, 0xbfb8aa3b
	s_mov_b32 s10, 0x3f2aaaab
	v_mov_b32_e32 v207, 0x3ecc95a3
	s_mov_b32 s11, 0x3f317218
	s_mov_b32 s33, 0x7f800000
	s_mov_b32 s78, 0x33800000
	s_mov_b32 s36, 0x40000
	s_mov_b32 s37, 0x48000
	s_mov_b32 s38, 0x50000
	v_mov_b32_e32 v208, 0x7f800000
	v_mov_b32_e32 v209, 0x7fc00000
	v_mov_b32_e32 v210, 0xff800000
	v_mov_b32_e32 v211, 0x3e38aa3b
	s_barrier
	v_writelane_b32 v254, s9, 58
	s_mov_b32 s101, 0
	s_branch .LBB0_426

.LBB0_428:
	s_ashr_i32 s95, s94, 31
	s_lshl_b64 s[16:17], s[94:95], 19
	s_add_u32 s96, s12, s16
	s_addc_u32 s97, s13, s17
	s_and_b64 s[16:17], s[8:9], exec
	s_cselect_b32 s15, s97, s89
	s_cselect_b32 s16, s96, s88
	s_ashr_i32 s85, s84, 31
	s_lshl_b64 s[18:19], s[84:85], 19
	s_add_u32 s90, s54, s18
	s_addc_u32 s91, s55, s19
	s_and_b64 s[18:19], s[8:9], exec
	s_cselect_b32 s17, s91, s7
	s_cselect_b32 s18, s90, s6
	s_add_u32 s88, s88, 0x40080
	s_addc_u32 s89, s89, 0
	s_add_u32 s19, s6, 0x100
	v_mov_b32_e32 v0, 0
	s_addc_u32 s20, s7, 0
	s_mov_b32 s21, -2
	s_waitcnt lgkmcnt(0)
	s_cmp_eq_u32 s101, 0
	s_cbranch_scc1 .Lpb_2
	s_barrier
	s_mov_b32 s101, 0
.Lpb_2:
.LBB0_429:
	ds_read_b128 v[128:131], v203
	ds_read_b128 v[132:135], v203 offset:1024
	ds_read_b128 v[136:139], v203 offset:2048
	ds_read_b128 v[164:167], v203 offset:3072
	ds_read_b128 v[168:171], v204
	ds_read_b128 v[172:175], v204 offset:1024
	ds_read_b128 v[176:179], v204 offset:2048
	ds_read_b128 v[180:183], v204 offset:3072
	s_add_u32 s6, s88, 0xfffc0080
	s_addc_u32 s7, s89, -1
	s_cmp_eq_u32 s21, 12
	s_cselect_b32 vcc_hi, s15, s7
	s_cselect_b32 vcc_lo, s16, s6
	s_cselect_b32 s7, s17, s20
	s_cselect_b32 s6, s18, s19
	v_lshl_add_u64 v[196:197], s[88:89], 0, v[156:157]
	s_add_i32 m0, s58, 0xc000
	ds_read_b128 v[184:187], v205
	ds_read_b128 v[188:191], v205 offset:1024
	ds_read_b128 v[192:195], v205 offset:2048
	ds_read_b128 v[212:215], v205 offset:3072
	ds_read_b128 v[216:219], v205 offset:4096
	ds_read_b128 v[220:223], v205 offset:5120
	ds_read_b128 v[224:227], v205 offset:6144
	ds_read_b128 v[228:231], v205 offset:7168
	global_load_lds_dwordx4 v[196:197], off
	s_add_i32 m0, s58, 0xe000
	v_lshl_add_u64 v[196:197], s[88:89], 0, v[158:159]
	global_load_lds_dwordx4 v[196:197], off
	s_cmp_eq_u32 s21, -2
	s_waitcnt vmcnt(8) lgkmcnt(0)
	s_barrier
	s_setprio 1
	s_cbranch_scc1 .Lzv_2_0
	v_mfma_f32_16x16x32_bf16 v[124:127], v[128:131], v[184:187], v[124:127]
	v_mfma_f32_16x16x32_bf16 v[124:127], v[132:135], v[188:191], v[124:127]
	v_mfma_f32_16x16x32_bf16 v[116:119], v[136:139], v[184:187], v[116:119]
	v_mfma_f32_16x16x32_bf16 v[116:119], v[164:167], v[188:191], v[116:119]
	v_mfma_f32_16x16x32_bf16 v[108:111], v[128:131], v[192:195], v[108:111]
	v_mfma_f32_16x16x32_bf16 v[108:111], v[132:135], v[212:215], v[108:111]
	v_mfma_f32_16x16x32_bf16 v[100:103], v[136:139], v[192:195], v[100:103]
	v_mfma_f32_16x16x32_bf16 v[100:103], v[164:167], v[212:215], v[100:103]
	v_mfma_f32_16x16x32_bf16 v[92:95], v[128:131], v[216:219], v[92:95]
	v_mfma_f32_16x16x32_bf16 v[92:95], v[132:135], v[220:223], v[92:95]
	v_mfma_f32_16x16x32_bf16 v[84:87], v[136:139], v[216:219], v[84:87]
	v_mfma_f32_16x16x32_bf16 v[84:87], v[164:167], v[220:223], v[84:87]
	v_mfma_f32_16x16x32_bf16 v[76:79], v[128:131], v[224:227], v[76:79]
	v_mfma_f32_16x16x32_bf16 v[76:79], v[132:135], v[228:231], v[76:79]
	v_mfma_f32_16x16x32_bf16 v[68:71], v[136:139], v[224:227], v[68:71]
	v_mfma_f32_16x16x32_bf16 v[68:71], v[164:167], v[228:231], v[68:71]
	v_mfma_f32_16x16x32_bf16 v[120:123], v[168:171], v[184:187], v[120:123]
	v_mfma_f32_16x16x32_bf16 v[120:123], v[172:175], v[188:191], v[120:123]
	v_mfma_f32_16x16x32_bf16 v[112:115], v[176:179], v[184:187], v[112:115]
	v_mfma_f32_16x16x32_bf16 v[112:115], v[180:183], v[188:191], v[112:115]
	v_mfma_f32_16x16x32_bf16 v[104:107], v[168:171], v[192:195], v[104:107]
	v_mfma_f32_16x16x32_bf16 v[104:107], v[172:175], v[212:215], v[104:107]
	v_mfma_f32_16x16x32_bf16 v[96:99], v[176:179], v[192:195], v[96:99]
	v_mfma_f32_16x16x32_bf16 v[96:99], v[180:183], v[212:215], v[96:99]
	v_mfma_f32_16x16x32_bf16 v[88:91], v[168:171], v[216:219], v[88:91]
	v_mfma_f32_16x16x32_bf16 v[88:91], v[172:175], v[220:223], v[88:91]
	v_mfma_f32_16x16x32_bf16 v[80:83], v[176:179], v[216:219], v[80:83]
	v_mfma_f32_16x16x32_bf16 v[80:83], v[180:183], v[220:223], v[80:83]
	v_mfma_f32_16x16x32_bf16 v[72:75], v[168:171], v[224:227], v[72:75]
	v_mfma_f32_16x16x32_bf16 v[72:75], v[172:175], v[228:231], v[72:75]
	s_setprio 3
	s_barrier
	v_mfma_f32_16x16x32_bf16 v[64:67], v[176:179], v[224:227], v[64:67]
	v_mfma_f32_16x16x32_bf16 v[64:67], v[180:183], v[228:231], v[64:67]
	s_setprio 0

.LBB0_451:
	s_andn2_b64 vcc, exec, s[26:27]
	s_cbranch_vccnz .LBB0_424
	s_mov_b32 s101, 1
	s_branch .LBB0_424

.LBB0_983:
	s_mov_b64 s[46:47], 0x80
	s_and_b32 s20, s5, 3
	s_add_i32 m0, s16, 0x18000
	v_lshl_add_u64 v[6:7], v[6:7], 0, s[46:47]
	s_lshl_b32 s5, s4, 13
	s_lshl_b32 s24, s20, 12
	s_waitcnt vmcnt(2)
	s_barrier
	global_load_lds_dwordx4 v[6:7], off
	v_lshl_add_u64 v[4:5], v[4:5], 0, s[46:47]
	s_add_i32 m0, s16, 0x1a000
	s_add_i32 s21, s16, 0x8000
	s_add_i32 s22, s16, 0xa000
	global_load_lds_dwordx4 v[4:5], off
	v_lshl_add_u64 v[0:1], v[0:1], 0, s[46:47]
	s_mov_b32 m0, s21
	s_add_u32 s6, s84, 0x40080
	global_load_lds_dwordx4 v[0:1], off
	v_lshl_add_u64 v[0:1], v[2:3], 0, s[46:47]
	s_mov_b32 m0, s22
	s_addc_u32 s7, s85, 0
	global_load_lds_dwordx4 v[0:1], off
	s_add_i32 m0, s16, 0x1c000
	v_lshl_add_u64 v[0:1], s[6:7], 0, v[194:195]
	global_load_lds_dwordx4 v[0:1], off
	v_lshl_add_u64 v[0:1], s[6:7], 0, v[198:199]
	s_add_i32 m0, s16, 0x1e000
	v_lshlrev_b32_e32 v4, 2, v240
	global_load_lds_dwordx4 v[0:1], off
	v_bfe_u32 v0, v240, 4, 2
	v_and_b32_e32 v1, 15, v240
	v_lshlrev_b32_e32 v3, 4, v0
	v_lshl_or_b32 v242, s4, 6, v1
	v_lshl_or_b32 v1, v1, 6, v3
	v_and_b32_e32 v4, 32, v4
	v_lshlrev_b32_e32 v5, 6, v240
	s_movk_i32 s4, 0x3c0
	v_lshlrev_b32_e32 v2, 3, v0
	v_bitop3_b32 v1, v1, s5, v4 bitop3:0xde
	v_and_or_b32 v3, v5, s4, v3
	v_cmp_eq_u32_e64 s[4:5], 0, v0
	v_lshlrev_b32_e32 v0, 8, v240
	v_lshl_or_b32 v244, s20, 5, v2
	v_and_b32_e32 v0, 0x38000, v0
	v_lshlrev_b32_e32 v2, 11, v10
	v_or3_b32 v0, v8, v0, v2
	v_add_u32_e32 v200, v0, v9
	v_lshlrev_b32_e32 v0, 4, v11
	v_and_b32_e32 v0, 0x78000, v0
	s_waitcnt vmcnt(6)
	s_cmpk_lt_u32 s23, 0x100
	v_or3_b32 v0, v8, v0, v2
	v_bitop3_b32 v243, s24, v3, v4 bitop3:0xf6
	s_cselect_b64 s[48:49], -1, 0
	v_add_u32_e32 v202, v0, v9
	s_add_i32 s26, 0, 0x10000
	s_add_i32 s27, 0, 0x14000
	v_mbcnt_lo_u32_b32 v0, -1, 0
	s_ashr_i32 s23, s34, 31
	s_mov_b32 s24, s34
	s_ashr_i32 s25, s2, 31
	v_mov_b32_e32 v201, v195
	v_mov_b32_e32 v203, v195
	v_add_u32_e32 v245, s26, v243
	v_add_u32_e32 v246, s27, v243
	v_add_u32_e32 v247, 0, v1
	v_mbcnt_hi_u32_b32 v248, -1, v0
	s_mov_b32 s33, 0
	s_barrier
	s_mov_b32 s101, 0
	s_branch .LBB0_986

.LBB0_992:
	s_ashr_i32 s53, s52, 31
	s_lshl_b64 s[54:55], s[52:53], 19
	s_add_u32 s76, s42, s54
	s_addc_u32 s77, s43, s55
	s_and_b64 s[54:55], s[6:7], exec
	s_cselect_b32 s53, s77, s83
	s_cselect_b32 s54, s76, s82
	s_ashr_i32 s51, s50, 31
	s_lshl_b64 s[56:57], s[50:51], 19
	s_add_u32 s78, s3, s56
	s_addc_u32 s79, s14, s57
	s_and_b64 s[56:57], s[6:7], exec
	s_cselect_b32 s51, s79, s85
	s_cselect_b32 s55, s78, s84
	s_add_u32 s82, s82, 0x40080
	s_addc_u32 s83, s83, 0
	s_add_u32 s56, s84, 0x100
	v_mov_b32_e32 v0, 0
	s_addc_u32 s57, s85, 0
	s_mov_b32 s58, -2
	s_cmp_eq_u32 s101, 0
	s_cbranch_scc1 .Lpb_3
	s_barrier
	s_mov_b32 s101, 0
.Lpb_3:
.LBB0_993:
	ds_read_b128 v[120:123], v245
	ds_read_b128 v[124:127], v245 offset:1024
	ds_read_b128 v[128:131], v245 offset:2048
	ds_read_b128 v[132:135], v245 offset:3072
	ds_read_b128 v[144:147], v246
	ds_read_b128 v[148:151], v246 offset:1024
	ds_read_b128 v[152:155], v246 offset:2048
	ds_read_b128 v[156:159], v246 offset:3072
	s_add_u32 s59, s82, 0xfffc0080
	s_addc_u32 s66, s83, -1
	s_cmp_eq_u32 s58, 12
	s_cselect_b32 s87, s53, s66
	s_cselect_b32 s86, s54, s59
	s_cselect_b32 s85, s51, s57
	s_cselect_b32 s84, s55, s56
	v_lshl_add_u64 v[204:205], s[82:83], 0, v[200:201]
	s_add_i32 m0, s16, 0xc000
	ds_read_b128 v[160:163], v247
	ds_read_b128 v[164:167], v247 offset:1024
	ds_read_b128 v[168:171], v247 offset:2048
	ds_read_b128 v[172:175], v247 offset:3072
	ds_read_b128 v[176:179], v247 offset:4096
	ds_read_b128 v[180:183], v247 offset:5120
	ds_read_b128 v[184:187], v247 offset:6144
	ds_read_b128 v[188:191], v247 offset:7168
	global_load_lds_dwordx4 v[204:205], off
	s_add_i32 m0, s16, 0xe000
	v_lshl_add_u64 v[204:205], s[82:83], 0, v[202:203]
	global_load_lds_dwordx4 v[204:205], off
	s_cmp_eq_u32 s58, -2
	s_waitcnt vmcnt(8) lgkmcnt(0)
	s_barrier
	s_setprio 1
	s_cbranch_scc1 .Lzv_3_0
	v_mfma_f32_16x16x32_bf16 v[140:143], v[120:123], v[160:163], v[140:143]
	v_mfma_f32_16x16x32_bf16 v[140:143], v[124:127], v[164:167], v[140:143]
	v_mfma_f32_16x16x32_bf16 v[136:139], v[128:131], v[160:163], v[136:139]
	v_mfma_f32_16x16x32_bf16 v[136:139], v[132:135], v[164:167], v[136:139]
	v_mfma_f32_16x16x32_bf16 v[108:111], v[120:123], v[168:171], v[108:111]
	v_mfma_f32_16x16x32_bf16 v[108:111], v[124:127], v[172:175], v[108:111]
	v_mfma_f32_16x16x32_bf16 v[104:107], v[128:131], v[168:171], v[104:107]
	v_mfma_f32_16x16x32_bf16 v[104:107], v[132:135], v[172:175], v[104:107]
	v_mfma_f32_16x16x32_bf16 v[92:95], v[120:123], v[176:179], v[92:95]
	v_mfma_f32_16x16x32_bf16 v[92:95], v[124:127], v[180:183], v[92:95]
	v_mfma_f32_16x16x32_bf16 v[88:91], v[128:131], v[176:179], v[88:91]
	v_mfma_f32_16x16x32_bf16 v[88:91], v[132:135], v[180:183], v[88:91]
	v_mfma_f32_16x16x32_bf16 v[76:79], v[120:123], v[184:187], v[76:79]
	v_mfma_f32_16x16x32_bf16 v[76:79], v[124:127], v[188:191], v[76:79]
	v_mfma_f32_16x16x32_bf16 v[72:75], v[128:131], v[184:187], v[72:75]
	v_mfma_f32_16x16x32_bf16 v[72:75], v[132:135], v[188:191], v[72:75]
	v_mfma_f32_16x16x32_bf16 v[116:119], v[144:147], v[160:163], v[116:119]
	v_mfma_f32_16x16x32_bf16 v[116:119], v[148:151], v[164:167], v[116:119]
	v_mfma_f32_16x16x32_bf16 v[112:115], v[152:155], v[160:163], v[112:115]
	v_mfma_f32_16x16x32_bf16 v[112:115], v[156:159], v[164:167], v[112:115]
	v_mfma_f32_16x16x32_bf16 v[100:103], v[144:147], v[168:171], v[100:103]
	v_mfma_f32_16x16x32_bf16 v[100:103], v[148:151], v[172:175], v[100:103]
	v_mfma_f32_16x16x32_bf16 v[96:99], v[152:155], v[168:171], v[96:99]
	v_mfma_f32_16x16x32_bf16 v[96:99], v[156:159], v[172:175], v[96:99]
	v_mfma_f32_16x16x32_bf16 v[84:87], v[144:147], v[176:179], v[84:87]
	v_mfma_f32_16x16x32_bf16 v[84:87], v[148:151], v[180:183], v[84:87]
	v_mfma_f32_16x16x32_bf16 v[80:83], v[152:155], v[176:179], v[80:83]
	v_mfma_f32_16x16x32_bf16 v[80:83], v[156:159], v[180:183], v[80:83]
	v_mfma_f32_16x16x32_bf16 v[68:71], v[144:147], v[184:187], v[68:71]
	v_mfma_f32_16x16x32_bf16 v[68:71], v[148:151], v[188:191], v[68:71]
	s_setprio 3
	s_barrier
	v_mfma_f32_16x16x32_bf16 v[64:67], v[152:155], v[184:187], v[64:67]
	v_mfma_f32_16x16x32_bf16 v[64:67], v[156:159], v[188:191], v[64:67]
	s_setprio 0

.LBB0_1012:
	s_or_b64 exec, exec, s[54:55]
	s_andn2_b64 vcc, exec, s[6:7]
	s_mov_b64 s[6:7], -1
	s_cbranch_vccnz .LBB0_985
	s_andn2_b64 vcc, exec, s[44:45]
	s_cbranch_vccnz .LBB0_984
	s_mov_b32 s101, 1
	s_branch .LBB0_984

.LBB0_1142:
	s_lshl_b32 s10, s23, 5
	s_and_b32 s33, s10, 0x60
	s_mov_b64 s[10:11], 0x80
	s_add_i32 m0, s17, 0x18000
	v_lshl_add_u64 v[6:7], v[6:7], 0, s[10:11]
	s_lshl_b32 s5, s4, 13
	s_lshl_b32 s45, s33, 7
	s_waitcnt vmcnt(2)
	s_barrier
	global_load_lds_dwordx4 v[6:7], off
	v_lshl_add_u64 v[4:5], v[4:5], 0, s[10:11]
	s_add_i32 m0, s17, 0x1a000
	s_add_i32 s23, s17, 0x8000
	s_add_i32 s24, s17, 0xa000
	global_load_lds_dwordx4 v[4:5], off
	v_lshl_add_u64 v[2:3], v[2:3], 0, s[10:11]
	s_mov_b32 m0, s23
	s_add_u32 s26, s80, 0x40080
	global_load_lds_dwordx4 v[2:3], off
	v_lshl_add_u64 v[0:1], v[0:1], 0, s[10:11]
	s_mov_b32 m0, s24
	s_addc_u32 s27, s81, 0
	global_load_lds_dwordx4 v[0:1], off
	s_add_i32 m0, s17, 0x1c000
	v_lshl_add_u64 v[0:1], s[26:27], 0, v[132:133]
	global_load_lds_dwordx4 v[0:1], off
	v_lshl_add_u64 v[0:1], s[26:27], 0, v[128:129]
	s_add_i32 m0, s17, 0x1e000
	v_mov_b32_e32 v137, 0
	global_load_lds_dwordx4 v[0:1], off
	v_and_b32_e32 v0, 15, v240
	v_bfe_u32 v1, v240, 4, 2
	v_lshl_or_b32 v170, s4, 6, v0
	s_lshl_b32 s4, s4, 8
	v_lshlrev_b32_e32 v136, 4, v1
	s_add_i32 s4, s4, 0
	v_lshl_or_b32 v2, v0, 6, v136
	v_lshlrev_b32_e32 v0, 2, v0
	s_add_i32 s4, s4, 0x20400
	v_and_b32_e32 v3, 32, v0
	v_add_u32_e32 v172, s4, v0
	v_lshlrev_b32_e32 v0, 8, v240
	v_lshl_or_b32 v173, v1, 3, s33
	v_and_b32_e32 v0, 0x38000, v0
	v_lshlrev_b32_e32 v1, 11, v15
	v_bitop3_b32 v2, v2, s5, v3 bitop3:0xde
	v_lshlrev_b32_e32 v3, 6, v240
	s_movk_i32 s5, 0x3c0
	v_or3_b32 v0, v13, v0, v1
	v_and_or_b32 v3, v3, s5, v136
	v_lshlrev_b32_e32 v4, 2, v240
	v_lshl_add_u64 v[138:139], s[70:71], 0, v[136:137]
	v_add_u32_e32 v136, v0, v14
	v_lshlrev_b32_e32 v0, 4, v12
	v_and_b32_e32 v4, 32, v4
	s_waitcnt vmcnt(6)
	s_cmpk_lt_u32 s25, 0x100
	v_and_b32_e32 v0, 0x78000, v0
	s_sext_i32_i8 s56, s44
	v_bitop3_b32 v171, s45, v3, v4 bitop3:0xf6
	s_cselect_b64 s[44:45], -1, 0
	v_or3_b32 v0, v13, v0, v1
	s_add_i32 s25, 0, 0x10000
	s_add_i32 s26, 0, 0x14000
	s_mov_b32 s57, 0
	v_add_u32_e32 v140, v0, v14
	v_mov_b32_e32 v141, v137
	v_mov_b64_e32 v[142:143], 0xb00
	v_mov_b64_e32 v[144:145], 0xaff
	v_add_u32_e32 v174, s25, v171
	v_add_u32_e32 v175, s26, v171
	v_add_u32_e32 v176, 0, v2
	v_mov_b32_e32 v177, 0x358637bd
	s_movk_i32 s27, 0x1600
	s_barrier
	s_mov_b32 s101, 0
	s_branch .LBB0_1145

.LBB0_1147:
	s_ashr_i32 s49, s48, 31
	s_lshl_b64 s[50:51], s[48:49], 19
	s_add_u32 s50, s12, s50
	s_addc_u32 s51, s13, s51
	s_and_b64 s[52:53], s[4:5], exec
	s_cselect_b32 s49, s51, s79
	s_cselect_b32 s54, s50, s78
	s_ashr_i32 s47, s46, 31
	s_lshl_b64 s[52:53], s[46:47], 19
	s_add_u32 s52, s14, s52
	s_addc_u32 s53, s15, s53
	s_and_b64 s[58:59], s[4:5], exec
	s_cselect_b32 s47, s53, s81
	s_cselect_b32 s55, s52, s80
	s_add_u32 s78, s78, 0x40080
	s_addc_u32 s79, s79, 0
	s_add_u32 s58, s80, 0x100
	v_mov_b32_e32 v0, 0
	s_addc_u32 s59, s81, 0
	s_mov_b32 s66, -2
	s_waitcnt lgkmcnt(0)
	s_cmp_eq_u32 s101, 0
	s_cbranch_scc1 .Lpb_4
	s_barrier
	s_mov_b32 s101, 0
.Lpb_4:
.LBB0_1148:
	ds_read_b128 v[146:149], v174
	ds_read_b128 v[150:153], v174 offset:1024
	ds_read_b128 v[154:157], v174 offset:2048
	ds_read_b128 v[158:161], v174 offset:3072
	ds_read_b128 v[162:165], v175
	ds_read_b128 v[178:181], v175 offset:1024
	ds_read_b128 v[182:185], v175 offset:2048
	ds_read_b128 v[186:189], v175 offset:3072
	s_add_u32 s67, s78, 0xfffc0080
	s_addc_u32 s68, s79, -1
	s_cmp_eq_u32 s66, 12
	s_cselect_b32 s83, s49, s68
	s_cselect_b32 s82, s54, s67
	s_cselect_b32 s81, s47, s59
	s_cselect_b32 s80, s55, s58
	v_lshl_add_u64 v[166:167], s[78:79], 0, v[136:137]
	s_add_i32 m0, s17, 0xc000
	ds_read_b128 v[190:193], v176
	ds_read_b128 v[194:197], v176 offset:1024
	ds_read_b128 v[198:201], v176 offset:2048
	ds_read_b128 v[202:205], v176 offset:3072
	ds_read_b128 v[206:209], v176 offset:4096
	ds_read_b128 v[210:213], v176 offset:5120
	ds_read_b128 v[214:217], v176 offset:6144
	ds_read_b128 v[218:221], v176 offset:7168
	global_load_lds_dwordx4 v[166:167], off
	s_add_i32 m0, s17, 0xe000
	v_lshl_add_u64 v[166:167], s[78:79], 0, v[140:141]
	global_load_lds_dwordx4 v[166:167], off
	s_cmp_eq_u32 s66, -2
	s_waitcnt vmcnt(8) lgkmcnt(0)
	s_barrier
	s_setprio 1
	s_cbranch_scc1 .Lzv_4_0
	v_mfma_f32_16x16x32_bf16 v[124:127], v[146:149], v[190:193], v[124:127]
	v_mfma_f32_16x16x32_bf16 v[124:127], v[150:153], v[194:197], v[124:127]
	v_mfma_f32_16x16x32_bf16 v[116:119], v[154:157], v[190:193], v[116:119]
	v_mfma_f32_16x16x32_bf16 v[116:119], v[158:161], v[194:197], v[116:119]
	v_mfma_f32_16x16x32_bf16 v[108:111], v[146:149], v[198:201], v[108:111]
	v_mfma_f32_16x16x32_bf16 v[108:111], v[150:153], v[202:205], v[108:111]
	v_mfma_f32_16x16x32_bf16 v[100:103], v[154:157], v[198:201], v[100:103]
	v_mfma_f32_16x16x32_bf16 v[100:103], v[158:161], v[202:205], v[100:103]
	v_mfma_f32_16x16x32_bf16 v[92:95], v[146:149], v[206:209], v[92:95]
	v_mfma_f32_16x16x32_bf16 v[92:95], v[150:153], v[210:213], v[92:95]
	v_mfma_f32_16x16x32_bf16 v[84:87], v[154:157], v[206:209], v[84:87]
	v_mfma_f32_16x16x32_bf16 v[84:87], v[158:161], v[210:213], v[84:87]
	v_mfma_f32_16x16x32_bf16 v[76:79], v[146:149], v[214:217], v[76:79]
	v_mfma_f32_16x16x32_bf16 v[76:79], v[150:153], v[218:221], v[76:79]
	v_mfma_f32_16x16x32_bf16 v[68:71], v[154:157], v[214:217], v[68:71]
	v_mfma_f32_16x16x32_bf16 v[68:71], v[158:161], v[218:221], v[68:71]
	v_mfma_f32_16x16x32_bf16 v[120:123], v[162:165], v[190:193], v[120:123]
	v_mfma_f32_16x16x32_bf16 v[120:123], v[178:181], v[194:197], v[120:123]
	v_mfma_f32_16x16x32_bf16 v[112:115], v[182:185], v[190:193], v[112:115]
	v_mfma_f32_16x16x32_bf16 v[112:115], v[186:189], v[194:197], v[112:115]
	v_mfma_f32_16x16x32_bf16 v[104:107], v[162:165], v[198:201], v[104:107]
	v_mfma_f32_16x16x32_bf16 v[104:107], v[178:181], v[202:205], v[104:107]
	v_mfma_f32_16x16x32_bf16 v[96:99], v[182:185], v[198:201], v[96:99]
	v_mfma_f32_16x16x32_bf16 v[96:99], v[186:189], v[202:205], v[96:99]
	v_mfma_f32_16x16x32_bf16 v[88:91], v[162:165], v[206:209], v[88:91]
	v_mfma_f32_16x16x32_bf16 v[88:91], v[178:181], v[210:213], v[88:91]
	v_mfma_f32_16x16x32_bf16 v[80:83], v[182:185], v[206:209], v[80:83]
	v_mfma_f32_16x16x32_bf16 v[80:83], v[186:189], v[210:213], v[80:83]
	v_mfma_f32_16x16x32_bf16 v[72:75], v[162:165], v[214:217], v[72:75]
	v_mfma_f32_16x16x32_bf16 v[72:75], v[178:181], v[218:221], v[72:75]
	s_setprio 3
	s_barrier
	v_mfma_f32_16x16x32_bf16 v[64:67], v[182:185], v[214:217], v[64:67]
	v_mfma_f32_16x16x32_bf16 v[64:67], v[186:189], v[218:221], v[64:67]
	s_setprio 0

.LBB0_1155:
	s_waitcnt lgkmcnt(0)
	v_mul_f32_e32 v164, 0xbfb8aa3b, v166
	v_mul_f32_e32 v147, v166, v166
	v_pk_mul_f32 v[178:179], v[126:127], v[164:165] op_sel_hi:[1,0]
	v_pk_mul_f32 v[122:123], v[126:127], v[122:123]
	v_pk_mul_f32 v[126:127], v[116:117], v[164:165] op_sel_hi:[1,0]
	v_rcp_f32_e32 v166, v147
	v_pk_mul_f32 v[180:181], v[124:125], v[164:165] op_sel_hi:[1,0]
	v_exp_f32_e32 v126, v126
	v_exp_f32_e32 v127, v127
	v_exp_f32_e32 v180, v180
	v_exp_f32_e32 v178, v178
	v_exp_f32_e32 v179, v179
	v_exp_f32_e32 v181, v181
	v_pk_mul_f32 v[120:121], v[124:125], v[120:121]
	v_pk_mul_f32 v[124:125], v[118:119], v[164:165] op_sel_hi:[1,0]
	v_pk_fma_f32 v[126:127], v[126:127], v[166:167], v[166:167] op_sel_hi:[1,0,0]
	v_exp_f32_e32 v124, v124
	v_exp_f32_e32 v125, v125
	v_pk_fma_f32 v[178:179], v[178:179], v[166:167], v[166:167] op_sel_hi:[1,0,0]
	v_pk_fma_f32 v[180:181], v[180:181], v[166:167], v[166:167] op_sel_hi:[1,0,0]
	v_rcp_f32_e32 v126, v126
	v_rcp_f32_e32 v127, v127
	v_rcp_f32_e32 v180, v180
	v_rcp_f32_e32 v181, v181
	v_rcp_f32_e32 v178, v178
	v_rcp_f32_e32 v179, v179
	v_pk_fma_f32 v[124:125], v[124:125], v[166:167], v[166:167] op_sel_hi:[1,0,0]
	v_pk_mul_f32 v[112:113], v[116:117], v[112:113]
	v_rcp_f32_e32 v124, v124
	v_rcp_f32_e32 v125, v125
	v_pk_mul_f32 v[112:113], v[112:113], v[126:127]
	v_pk_mul_f32 v[122:123], v[122:123], v[178:179]
	v_pk_mul_f32 v[120:121], v[120:121], v[180:181]
	v_pk_mul_f32 v[114:115], v[118:119], v[114:115]
	v_cvt_pk_bf16_f32 v116, v120, v121
	v_cvt_pk_bf16_f32 v117, v122, v123
	v_cvt_pk_bf16_f32 v118, v112, v113
	v_mov_b64_e32 v[112:113], s[64:65]
	v_pk_mul_f32 v[114:115], v[114:115], v[124:125]
	v_mad_u64_u32 v[120:121], s[54:55], v160, s27, v[112:113]
	v_cvt_pk_bf16_f32 v119, v114, v115
	v_mov_b32_e32 v114, v121
	v_mul_f32_e32 v122, 0xbfb8aa3b, v167
	v_mul_f32_e32 v123, v167, v167
	v_mad_u64_u32 v[114:115], s[54:55], v161, s27, v[114:115]
	v_pk_mul_f32 v[126:127], v[110:111], v[122:123] op_sel_hi:[1,0]
	v_pk_mul_f32 v[160:161], v[108:109], v[122:123] op_sel_hi:[1,0]
	v_pk_mul_f32 v[106:107], v[110:111], v[106:107]
	v_pk_mul_f32 v[104:105], v[108:109], v[104:105]
	v_pk_mul_f32 v[108:109], v[102:103], v[122:123] op_sel_hi:[1,0]
	v_pk_mul_f32 v[110:111], v[100:101], v[122:123] op_sel_hi:[1,0]
	v_rcp_f32_e32 v124, v123
	v_exp_f32_e32 v110, v110
	v_exp_f32_e32 v108, v108
	v_exp_f32_e32 v109, v109
	v_exp_f32_e32 v111, v111
	v_lshl_or_b32 v182, s56, 7, v173
	v_exp_f32_e32 v160, v160
	v_exp_f32_e32 v126, v126
	v_exp_f32_e32 v127, v127
	v_exp_f32_e32 v161, v161
	v_ashrrev_i32_e32 v183, 31, v182
	v_mov_b32_e32 v121, v114
	v_lshlrev_b64 v[114:115], 1, v[182:183]
	v_lshl_add_u64 v[120:121], v[120:121], 0, v[114:115]
	v_pk_fma_f32 v[108:109], v[108:109], v[124:125], v[124:125] op_sel_hi:[1,0,0]
	v_pk_fma_f32 v[110:111], v[110:111], v[124:125], v[124:125] op_sel_hi:[1,0,0]
	global_store_dwordx4 v[120:121], v[116:119], off
	v_rcp_f32_e32 v110, v110
	v_rcp_f32_e32 v108, v108
	v_pk_fma_f32 v[116:117], v[126:127], v[124:125], v[124:125] op_sel_hi:[1,0,0]
	v_pk_fma_f32 v[118:119], v[160:161], v[124:125], v[124:125] op_sel_hi:[1,0,0]
	v_rcp_f32_e32 v109, v109
	v_rcp_f32_e32 v111, v111
	v_rcp_f32_e32 v118, v118
	v_rcp_f32_e32 v119, v119
	v_rcp_f32_e32 v116, v116
	v_rcp_f32_e32 v117, v117
	v_pk_mul_f32 v[98:99], v[102:103], v[98:99]
	v_pk_mul_f32 v[96:97], v[100:101], v[96:97]
	v_pk_mul_f32 v[100:101], v[98:99], v[108:109]
	v_pk_mul_f32 v[98:99], v[96:97], v[110:111]
	v_pk_mul_f32 v[106:107], v[106:107], v[116:117]
	v_pk_mul_f32 v[104:105], v[104:105], v[118:119]
	v_pk_mul_f32 v[90:91], v[94:95], v[90:91]
	v_cvt_pk_bf16_f32 v96, v104, v105
	v_cvt_pk_bf16_f32 v97, v106, v107
	v_cvt_pk_bf16_f32 v98, v98, v99
	v_cvt_pk_bf16_f32 v99, v100, v101
	v_mad_u64_u32 v[100:101], s[54:55], v156, s27, v[112:113]
	v_mul_f32_e32 v102, 0xbfb8aa3b, v162
	v_mul_f32_e32 v103, v162, v162
	v_pk_mul_f32 v[106:107], v[94:95], v[102:103] op_sel_hi:[1,0]
	v_pk_mul_f32 v[108:109], v[92:93], v[102:103] op_sel_hi:[1,0]
	v_pk_mul_f32 v[88:89], v[92:93], v[88:89]
	v_pk_mul_f32 v[92:93], v[86:87], v[102:103] op_sel_hi:[1,0]
	v_pk_mul_f32 v[94:95], v[84:85], v[102:103] op_sel_hi:[1,0]
	v_rcp_f32_e32 v104, v103
	v_exp_f32_e32 v94, v94
	v_exp_f32_e32 v92, v92
	v_exp_f32_e32 v93, v93
	v_exp_f32_e32 v95, v95
	v_exp_f32_e32 v108, v108
	v_exp_f32_e32 v106, v106
	v_exp_f32_e32 v107, v107
	v_exp_f32_e32 v109, v109
	v_lshl_add_u64 v[100:101], v[100:101], 0, v[114:115]
	v_pk_fma_f32 v[92:93], v[92:93], v[104:105], v[104:105] op_sel_hi:[1,0,0]
	v_pk_fma_f32 v[94:95], v[94:95], v[104:105], v[104:105] op_sel_hi:[1,0,0]
	global_store_dwordx4 v[100:101], v[96:99], off
	v_rcp_f32_e32 v94, v94
	v_rcp_f32_e32 v92, v92
	v_pk_fma_f32 v[96:97], v[106:107], v[104:105], v[104:105] op_sel_hi:[1,0,0]
	v_pk_fma_f32 v[98:99], v[108:109], v[104:105], v[104:105] op_sel_hi:[1,0,0]
	v_rcp_f32_e32 v93, v93
	v_rcp_f32_e32 v95, v95
	v_rcp_f32_e32 v98, v98
	v_rcp_f32_e32 v99, v99
	v_rcp_f32_e32 v96, v96
	v_rcp_f32_e32 v97, v97
	v_pk_mul_f32 v[82:83], v[86:87], v[82:83]
	v_pk_mul_f32 v[80:81], v[84:85], v[80:81]
	v_pk_mul_f32 v[84:85], v[82:83], v[92:93]
	v_pk_mul_f32 v[82:83], v[80:81], v[94:95]
	v_pk_mul_f32 v[90:91], v[90:91], v[96:97]
	v_pk_mul_f32 v[88:89], v[88:89], v[98:99]
	v_pk_mul_f32 v[74:75], v[78:79], v[74:75]
	v_cvt_pk_bf16_f32 v80, v88, v89
	v_cvt_pk_bf16_f32 v81, v90, v91
	v_cvt_pk_bf16_f32 v82, v82, v83
	v_cvt_pk_bf16_f32 v83, v84, v85
	v_mad_u64_u32 v[84:85], s[54:55], v152, s27, v[112:113]
	v_mul_f32_e32 v86, 0xbfb8aa3b, v163
	v_mul_f32_e32 v87, v163, v163
	v_pk_mul_f32 v[90:91], v[78:79], v[86:87] op_sel_hi:[1,0]
	v_pk_mul_f32 v[92:93], v[76:77], v[86:87] op_sel_hi:[1,0]
	v_pk_mul_f32 v[72:73], v[76:77], v[72:73]
	v_pk_mul_f32 v[76:77], v[70:71], v[86:87] op_sel_hi:[1,0]
	v_pk_mul_f32 v[78:79], v[68:69], v[86:87] op_sel_hi:[1,0]
	v_rcp_f32_e32 v88, v87
	v_exp_f32_e32 v78, v78
	v_exp_f32_e32 v76, v76
	v_exp_f32_e32 v77, v77
	v_exp_f32_e32 v79, v79
	v_exp_f32_e32 v92, v92
	v_exp_f32_e32 v90, v90
	v_exp_f32_e32 v91, v91
	v_exp_f32_e32 v93, v93
	v_lshl_add_u64 v[84:85], v[84:85], 0, v[114:115]
	v_pk_fma_f32 v[76:77], v[76:77], v[88:89], v[88:89] op_sel_hi:[1,0,0]
	v_pk_fma_f32 v[78:79], v[78:79], v[88:89], v[88:89] op_sel_hi:[1,0,0]
	global_store_dwordx4 v[84:85], v[80:83], off
	v_rcp_f32_e32 v78, v78
	v_rcp_f32_e32 v76, v76
	v_pk_fma_f32 v[80:81], v[90:91], v[88:89], v[88:89] op_sel_hi:[1,0,0]
	v_pk_fma_f32 v[82:83], v[92:93], v[88:89], v[88:89] op_sel_hi:[1,0,0]
	v_rcp_f32_e32 v77, v77
	v_rcp_f32_e32 v79, v79
	v_rcp_f32_e32 v82, v82
	v_rcp_f32_e32 v83, v83
	v_rcp_f32_e32 v80, v80
	v_rcp_f32_e32 v81, v81
	v_pk_mul_f32 v[66:67], v[70:71], v[66:67]
	v_pk_mul_f32 v[64:65], v[68:69], v[64:65]
	v_pk_mul_f32 v[68:69], v[66:67], v[76:77]
	v_pk_mul_f32 v[66:67], v[64:65], v[78:79]
	v_pk_mul_f32 v[74:75], v[74:75], v[80:81]
	v_pk_mul_f32 v[72:73], v[72:73], v[82:83]
	v_pk_mul_f32 v[58:59], v[62:63], v[58:59]
	v_cvt_pk_bf16_f32 v64, v72, v73
	v_cvt_pk_bf16_f32 v65, v74, v75
	v_cvt_pk_bf16_f32 v66, v66, v67
	v_cvt_pk_bf16_f32 v67, v68, v69
	v_mad_u64_u32 v[68:69], s[54:55], v150, s27, v[112:113]
	v_mul_f32_e32 v70, 0xbfb8aa3b, v154
	v_mul_f32_e32 v71, v154, v154
	v_pk_mul_f32 v[74:75], v[62:63], v[70:71] op_sel_hi:[1,0]
	v_pk_mul_f32 v[76:77], v[60:61], v[70:71] op_sel_hi:[1,0]
	v_pk_mul_f32 v[56:57], v[60:61], v[56:57]
	v_pk_mul_f32 v[60:61], v[54:55], v[70:71] op_sel_hi:[1,0]
	v_pk_mul_f32 v[62:63], v[52:53], v[70:71] op_sel_hi:[1,0]
	v_rcp_f32_e32 v72, v71
	v_exp_f32_e32 v62, v62
	v_exp_f32_e32 v60, v60
	v_exp_f32_e32 v61, v61
	v_exp_f32_e32 v63, v63
	v_exp_f32_e32 v76, v76
	v_exp_f32_e32 v74, v74
	v_exp_f32_e32 v75, v75
	v_exp_f32_e32 v77, v77
	v_lshl_add_u64 v[68:69], v[68:69], 0, v[114:115]
	v_pk_fma_f32 v[60:61], v[60:61], v[72:73], v[72:73] op_sel_hi:[1,0,0]
	v_pk_fma_f32 v[62:63], v[62:63], v[72:73], v[72:73] op_sel_hi:[1,0,0]
	global_store_dwordx4 v[68:69], v[64:67], off
	v_rcp_f32_e32 v62, v62
	v_rcp_f32_e32 v60, v60
	v_pk_fma_f32 v[64:65], v[74:75], v[72:73], v[72:73] op_sel_hi:[1,0,0]
	v_pk_fma_f32 v[66:67], v[76:77], v[72:73], v[72:73] op_sel_hi:[1,0,0]
	v_rcp_f32_e32 v61, v61
	v_rcp_f32_e32 v63, v63
	v_rcp_f32_e32 v66, v66
	v_rcp_f32_e32 v67, v67
	v_rcp_f32_e32 v64, v64
	v_rcp_f32_e32 v65, v65
	v_pk_mul_f32 v[50:51], v[54:55], v[50:51]
	v_pk_mul_f32 v[48:49], v[52:53], v[48:49]
	v_pk_mul_f32 v[52:53], v[50:51], v[60:61]
	v_pk_mul_f32 v[50:51], v[48:49], v[62:63]
	v_pk_mul_f32 v[58:59], v[58:59], v[64:65]
	v_pk_mul_f32 v[56:57], v[56:57], v[66:67]
	v_pk_mul_f32 v[42:43], v[46:47], v[42:43]
	v_cvt_pk_bf16_f32 v48, v56, v57
	v_cvt_pk_bf16_f32 v49, v58, v59
	v_cvt_pk_bf16_f32 v50, v50, v51
	v_cvt_pk_bf16_f32 v51, v52, v53
	v_mad_u64_u32 v[52:53], s[54:55], v158, s27, v[112:113]
	v_mov_b32_e32 v54, v53
	v_mad_u64_u32 v[54:55], s[54:55], v159, s27, v[54:55]
	v_mov_b32_e32 v53, v54
	v_mul_f32_e32 v54, 0xbfb8aa3b, v155
	v_mul_f32_e32 v55, v155, v155
	v_pk_mul_f32 v[58:59], v[46:47], v[54:55] op_sel_hi:[1,0]
	v_pk_mul_f32 v[60:61], v[44:45], v[54:55] op_sel_hi:[1,0]
	v_pk_mul_f32 v[40:41], v[44:45], v[40:41]
	v_pk_mul_f32 v[44:45], v[38:39], v[54:55] op_sel_hi:[1,0]
	v_pk_mul_f32 v[46:47], v[36:37], v[54:55] op_sel_hi:[1,0]
	v_rcp_f32_e32 v56, v55
	v_exp_f32_e32 v46, v46
	v_exp_f32_e32 v44, v44
	v_exp_f32_e32 v45, v45
	v_exp_f32_e32 v47, v47
	v_exp_f32_e32 v60, v60
	v_exp_f32_e32 v58, v58
	v_exp_f32_e32 v59, v59
	v_exp_f32_e32 v61, v61
	v_lshl_add_u64 v[52:53], v[52:53], 0, v[114:115]
	v_pk_fma_f32 v[44:45], v[44:45], v[56:57], v[56:57] op_sel_hi:[1,0,0]
	v_pk_fma_f32 v[46:47], v[46:47], v[56:57], v[56:57] op_sel_hi:[1,0,0]
	global_store_dwordx4 v[52:53], v[48:51], off
	v_rcp_f32_e32 v46, v46
	v_rcp_f32_e32 v44, v44
	v_pk_fma_f32 v[48:49], v[58:59], v[56:57], v[56:57] op_sel_hi:[1,0,0]
	v_pk_fma_f32 v[50:51], v[60:61], v[56:57], v[56:57] op_sel_hi:[1,0,0]
	v_rcp_f32_e32 v45, v45
	v_rcp_f32_e32 v47, v47
	v_rcp_f32_e32 v50, v50
	v_rcp_f32_e32 v51, v51
	v_rcp_f32_e32 v48, v48
	v_rcp_f32_e32 v49, v49
	v_pk_mul_f32 v[34:35], v[38:39], v[34:35]
	v_pk_mul_f32 v[32:33], v[36:37], v[32:33]
	v_pk_mul_f32 v[36:37], v[34:35], v[44:45]
	v_pk_mul_f32 v[34:35], v[32:33], v[46:47]
	v_add_u32_e32 v38, 16, v146
	v_pk_mul_f32 v[42:43], v[42:43], v[48:49]
	v_pk_mul_f32 v[40:41], v[40:41], v[50:51]
	v_mul_f32_e32 v39, v148, v148
	v_cvt_pk_bf16_f32 v32, v40, v41
	v_cvt_pk_bf16_f32 v33, v42, v43
	v_cvt_pk_bf16_f32 v34, v34, v35
	v_cvt_pk_bf16_f32 v35, v36, v37
	v_mad_i64_i32 v[36:37], s[54:55], v38, s27, v[112:113]
	v_mul_f32_e32 v38, 0xbfb8aa3b, v148
	v_pk_mul_f32 v[42:43], v[30:31], v[38:39] op_sel_hi:[1,0]
	v_pk_mul_f32 v[44:45], v[28:29], v[38:39] op_sel_hi:[1,0]
	v_pk_mul_f32 v[26:27], v[30:31], v[26:27]
	v_pk_mul_f32 v[24:25], v[28:29], v[24:25]
	v_pk_mul_f32 v[28:29], v[22:23], v[38:39] op_sel_hi:[1,0]
	v_pk_mul_f32 v[30:31], v[20:21], v[38:39] op_sel_hi:[1,0]
	v_rcp_f32_e32 v40, v39
	v_exp_f32_e32 v30, v30
	v_exp_f32_e32 v28, v28
	v_exp_f32_e32 v29, v29
	v_exp_f32_e32 v31, v31
	v_exp_f32_e32 v44, v44
	v_exp_f32_e32 v42, v42
	v_exp_f32_e32 v43, v43
	v_exp_f32_e32 v45, v45
	v_lshl_add_u64 v[36:37], v[36:37], 0, v[114:115]
	v_pk_fma_f32 v[28:29], v[28:29], v[40:41], v[40:41] op_sel_hi:[1,0,0]
	v_pk_fma_f32 v[30:31], v[30:31], v[40:41], v[40:41] op_sel_hi:[1,0,0]
	global_store_dwordx4 v[36:37], v[32:35], off
	v_rcp_f32_e32 v30, v30
	v_rcp_f32_e32 v28, v28
	v_pk_fma_f32 v[32:33], v[42:43], v[40:41], v[40:41] op_sel_hi:[1,0,0]
	v_pk_fma_f32 v[34:35], v[44:45], v[40:41], v[40:41] op_sel_hi:[1,0,0]
	v_rcp_f32_e32 v29, v29
	v_rcp_f32_e32 v31, v31
	v_rcp_f32_e32 v34, v34
	v_rcp_f32_e32 v35, v35
	v_rcp_f32_e32 v32, v32
	v_rcp_f32_e32 v33, v33
	v_pk_mul_f32 v[18:19], v[22:23], v[18:19]
	v_pk_mul_f32 v[16:17], v[20:21], v[16:17]
	v_pk_mul_f32 v[20:21], v[18:19], v[28:29]
	v_pk_mul_f32 v[18:19], v[16:17], v[30:31]
	v_add_u32_e32 v22, 32, v146
	v_pk_mul_f32 v[26:27], v[26:27], v[32:33]
	v_pk_mul_f32 v[24:25], v[24:25], v[34:35]
	v_mul_f32_e32 v23, v149, v149
	v_cvt_pk_bf16_f32 v16, v24, v25
	v_cvt_pk_bf16_f32 v17, v26, v27
	v_cvt_pk_bf16_f32 v18, v18, v19
	v_cvt_pk_bf16_f32 v19, v20, v21
	v_mad_i64_i32 v[20:21], s[54:55], v22, s27, v[112:113]
	v_mul_f32_e32 v22, 0xbfb8aa3b, v149
	v_pk_mul_f32 v[26:27], v[14:15], v[22:23] op_sel_hi:[1,0]
	v_pk_mul_f32 v[28:29], v[12:13], v[22:23] op_sel_hi:[1,0]
	v_pk_mul_f32 v[10:11], v[14:15], v[10:11]
	v_pk_mul_f32 v[8:9], v[12:13], v[8:9]
	v_pk_mul_f32 v[12:13], v[6:7], v[22:23] op_sel_hi:[1,0]
	v_pk_mul_f32 v[14:15], v[4:5], v[22:23] op_sel_hi:[1,0]
	v_rcp_f32_e32 v24, v23
	v_exp_f32_e32 v14, v14
	v_exp_f32_e32 v12, v12
	v_exp_f32_e32 v13, v13
	v_exp_f32_e32 v15, v15
	v_exp_f32_e32 v28, v28
	v_exp_f32_e32 v26, v26
	v_exp_f32_e32 v27, v27
	v_exp_f32_e32 v29, v29
	v_lshl_add_u64 v[20:21], v[20:21], 0, v[114:115]
	v_pk_fma_f32 v[12:13], v[12:13], v[24:25], v[24:25] op_sel_hi:[1,0,0]
	v_pk_fma_f32 v[14:15], v[14:15], v[24:25], v[24:25] op_sel_hi:[1,0,0]
	global_store_dwordx4 v[20:21], v[16:19], off
	v_rcp_f32_e32 v14, v14
	v_rcp_f32_e32 v12, v12
	v_pk_fma_f32 v[16:17], v[26:27], v[24:25], v[24:25] op_sel_hi:[1,0,0]
	v_pk_fma_f32 v[18:19], v[28:29], v[24:25], v[24:25] op_sel_hi:[1,0,0]
	v_rcp_f32_e32 v13, v13
	v_rcp_f32_e32 v15, v15
	v_rcp_f32_e32 v18, v18
	v_rcp_f32_e32 v19, v19
	v_rcp_f32_e32 v16, v16
	v_rcp_f32_e32 v17, v17
	v_pk_mul_f32 v[2:3], v[6:7], v[2:3]
	v_pk_mul_f32 v[0:1], v[4:5], v[0:1]
	v_pk_mul_f32 v[4:5], v[2:3], v[12:13]
	v_pk_mul_f32 v[2:3], v[0:1], v[14:15]
	v_add_u32_e32 v6, 48, v146
	v_pk_mul_f32 v[10:11], v[10:11], v[16:17]
	v_pk_mul_f32 v[8:9], v[8:9], v[18:19]
	s_andn2_b64 vcc, exec, s[4:5]
	v_cvt_pk_bf16_f32 v0, v8, v9
	v_cvt_pk_bf16_f32 v1, v10, v11
	v_cvt_pk_bf16_f32 v2, v2, v3
	v_cvt_pk_bf16_f32 v3, v4, v5
	v_mad_i64_i32 v[4:5], s[54:55], v6, s27, v[112:113]
	v_lshl_add_u64 v[4:5], v[4:5], 0, v[114:115]
	s_mov_b64 s[4:5], -1
	global_store_dwordx4 v[4:5], v[0:3], off
	s_cbranch_vccnz .LBB0_1144
	s_andn2_b64 vcc, exec, s[8:9]
	s_cbranch_vccnz .LBB0_1143
	s_mov_b32 s101, 1
	s_branch .LBB0_1143

.LBB0_1285:
	s_mov_b64 s[48:49], 0x80
	s_and_b32 s20, s5, 3
	s_add_i32 m0, s16, 0x18000
	v_lshl_add_u64 v[6:7], v[6:7], 0, s[48:49]
	s_lshl_b32 s5, s4, 13
	s_lshl_b32 s9, s20, 12
	s_waitcnt vmcnt(2)
	s_barrier
	global_load_lds_dwordx4 v[6:7], off
	v_lshl_add_u64 v[4:5], v[4:5], 0, s[48:49]
	s_add_i32 m0, s16, 0x1a000
	s_add_i32 s21, s16, 0x8000
	s_add_i32 s22, s16, 0xa000
	global_load_lds_dwordx4 v[4:5], off
	v_lshl_add_u64 v[0:1], v[0:1], 0, s[48:49]
	s_mov_b32 m0, s21
	s_add_u32 s6, s78, 0xb0080
	global_load_lds_dwordx4 v[0:1], off
	v_lshl_add_u64 v[0:1], v[2:3], 0, s[48:49]
	s_mov_b32 m0, s22
	s_addc_u32 s7, s79, 0
	global_load_lds_dwordx4 v[0:1], off
	s_add_i32 m0, s16, 0x1c000
	v_lshl_add_u64 v[0:1], s[6:7], 0, v[194:195]
	global_load_lds_dwordx4 v[0:1], off
	v_lshl_add_u64 v[0:1], s[6:7], 0, v[198:199]
	s_add_i32 m0, s16, 0x1e000
	v_lshlrev_b32_e32 v4, 2, v240
	global_load_lds_dwordx4 v[0:1], off
	v_bfe_u32 v0, v240, 4, 2
	v_and_b32_e32 v1, 15, v240
	v_lshlrev_b32_e32 v3, 4, v0
	v_lshl_or_b32 v242, s4, 6, v1
	v_lshl_or_b32 v1, v1, 6, v3
	v_and_b32_e32 v4, 32, v4
	v_lshlrev_b32_e32 v5, 6, v240
	s_movk_i32 s4, 0x3c0
	v_lshlrev_b32_e32 v2, 3, v0
	v_bitop3_b32 v1, v1, s5, v4 bitop3:0xde
	v_and_or_b32 v3, v5, s4, v3
	v_cmp_eq_u32_e64 s[4:5], 0, v0
	v_add_u16_e32 v0, v8, v9
	s_waitcnt vmcnt(6)
	s_cmpk_lt_u32 s8, 0x100
	v_lshrrev_b16_e32 v0, 1, v0
	v_bitop3_b32 v243, s9, v3, v4 bitop3:0xf6
	s_cselect_b64 s[50:51], -1, 0
	v_add_lshl_u32 v200, v10, v0, 1
	v_add_lshl_u32 v202, v11, v0, 1
	s_add_i32 s26, 0, 0x10000
	s_add_i32 s27, 0, 0x14000
	v_mbcnt_lo_u32_b32 v0, -1, 0
	v_lshl_or_b32 v244, s20, 5, v2
	s_ashr_i32 s23, s34, 31
	s_mov_b32 s24, s34
	s_ashr_i32 s25, s2, 31
	v_mov_b32_e32 v201, v195
	v_mov_b32_e32 v203, v195
	v_add_u32_e32 v245, s26, v243
	v_add_u32_e32 v246, s27, v243
	v_add_u32_e32 v247, 0, v1
	v_mbcnt_hi_u32_b32 v248, -1, v0
	s_mov_b32 s33, 0
	s_barrier
	s_mov_b32 s101, 0
	s_branch .LBB0_1288

.LBB0_1298:
	s_add_u32 s76, s76, 0xb0080
	s_addc_u32 s77, s77, 0
	s_add_u32 s55, s78, 0x100
	v_mov_b32_e32 v0, 0
	s_addc_u32 s58, s79, 0
	s_mov_b32 s59, -2
	s_cmp_eq_u32 s101, 0
	s_cbranch_scc1 .Lpb_5
	s_barrier
	s_mov_b32 s101, 0
.Lpb_5:
.LBB0_1299:
	ds_read_b128 v[120:123], v245
	ds_read_b128 v[124:127], v245 offset:1024
	ds_read_b128 v[128:131], v245 offset:2048
	ds_read_b128 v[132:135], v245 offset:3072
	ds_read_b128 v[144:147], v246
	ds_read_b128 v[148:151], v246 offset:1024
	ds_read_b128 v[152:155], v246 offset:2048
	ds_read_b128 v[156:159], v246 offset:3072
	s_add_u32 s66, s76, 0xfff50080
	s_addc_u32 s67, s77, -1
	s_cmp_eq_u32 s59, 40
	s_cselect_b32 s81, s9, s67
	s_cselect_b32 s80, s8, s66
	s_cselect_b32 s79, s53, s58
	s_cselect_b32 s78, s52, s55
	v_lshl_add_u64 v[204:205], s[76:77], 0, v[200:201]
	s_add_i32 m0, s16, 0xc000
	ds_read_b128 v[160:163], v247
	ds_read_b128 v[164:167], v247 offset:1024
	ds_read_b128 v[168:171], v247 offset:2048
	ds_read_b128 v[172:175], v247 offset:3072
	ds_read_b128 v[176:179], v247 offset:4096
	ds_read_b128 v[180:183], v247 offset:5120
	ds_read_b128 v[184:187], v247 offset:6144
	ds_read_b128 v[188:191], v247 offset:7168
	global_load_lds_dwordx4 v[204:205], off
	s_add_i32 m0, s16, 0xe000
	v_lshl_add_u64 v[204:205], s[76:77], 0, v[202:203]
	global_load_lds_dwordx4 v[204:205], off
	s_cmp_eq_u32 s59, -2
	s_waitcnt vmcnt(8) lgkmcnt(0)
	s_barrier
	s_setprio 1
	s_cbranch_scc1 .Lzv_5_0
	v_mfma_f32_16x16x32_bf16 v[140:143], v[120:123], v[160:163], v[140:143]
	v_mfma_f32_16x16x32_bf16 v[140:143], v[124:127], v[164:167], v[140:143]
	v_mfma_f32_16x16x32_bf16 v[136:139], v[128:131], v[160:163], v[136:139]
	v_mfma_f32_16x16x32_bf16 v[136:139], v[132:135], v[164:167], v[136:139]
	v_mfma_f32_16x16x32_bf16 v[108:111], v[120:123], v[168:171], v[108:111]
	v_mfma_f32_16x16x32_bf16 v[108:111], v[124:127], v[172:175], v[108:111]
	v_mfma_f32_16x16x32_bf16 v[104:107], v[128:131], v[168:171], v[104:107]
	v_mfma_f32_16x16x32_bf16 v[104:107], v[132:135], v[172:175], v[104:107]
	v_mfma_f32_16x16x32_bf16 v[92:95], v[120:123], v[176:179], v[92:95]
	v_mfma_f32_16x16x32_bf16 v[92:95], v[124:127], v[180:183], v[92:95]
	v_mfma_f32_16x16x32_bf16 v[88:91], v[128:131], v[176:179], v[88:91]
	v_mfma_f32_16x16x32_bf16 v[88:91], v[132:135], v[180:183], v[88:91]
	v_mfma_f32_16x16x32_bf16 v[76:79], v[120:123], v[184:187], v[76:79]
	v_mfma_f32_16x16x32_bf16 v[76:79], v[124:127], v[188:191], v[76:79]
	v_mfma_f32_16x16x32_bf16 v[72:75], v[128:131], v[184:187], v[72:75]
	v_mfma_f32_16x16x32_bf16 v[72:75], v[132:135], v[188:191], v[72:75]
	v_mfma_f32_16x16x32_bf16 v[116:119], v[144:147], v[160:163], v[116:119]
	v_mfma_f32_16x16x32_bf16 v[116:119], v[148:151], v[164:167], v[116:119]
	v_mfma_f32_16x16x32_bf16 v[112:115], v[152:155], v[160:163], v[112:115]
	v_mfma_f32_16x16x32_bf16 v[112:115], v[156:159], v[164:167], v[112:115]
	v_mfma_f32_16x16x32_bf16 v[100:103], v[144:147], v[168:171], v[100:103]
	v_mfma_f32_16x16x32_bf16 v[100:103], v[148:151], v[172:175], v[100:103]
	v_mfma_f32_16x16x32_bf16 v[96:99], v[152:155], v[168:171], v[96:99]
	v_mfma_f32_16x16x32_bf16 v[96:99], v[156:159], v[172:175], v[96:99]
	v_mfma_f32_16x16x32_bf16 v[84:87], v[144:147], v[176:179], v[84:87]
	v_mfma_f32_16x16x32_bf16 v[84:87], v[148:151], v[180:183], v[84:87]
	v_mfma_f32_16x16x32_bf16 v[80:83], v[152:155], v[176:179], v[80:83]
	v_mfma_f32_16x16x32_bf16 v[80:83], v[156:159], v[180:183], v[80:83]
	v_mfma_f32_16x16x32_bf16 v[68:71], v[144:147], v[184:187], v[68:71]
	v_mfma_f32_16x16x32_bf16 v[68:71], v[148:151], v[188:191], v[68:71]
	s_setprio 3
	s_barrier
	v_mfma_f32_16x16x32_bf16 v[64:67], v[152:155], v[184:187], v[64:67]
	v_mfma_f32_16x16x32_bf16 v[64:67], v[156:159], v[188:191], v[64:67]
	s_setprio 0

.LBB0_1318:
	s_or_b64 exec, exec, s[54:55]
	s_and_b64 vcc, exec, s[6:7]
	s_mov_b64 s[6:7], -1
	s_cbranch_vccnz .LBB0_1287
	s_andn2_b64 vcc, exec, s[46:47]
	s_cbranch_vccnz .LBB0_1286
	s_mov_b32 s101, 1
	s_branch .LBB0_1286

.LBB0_1754:
	s_lshl_b32 s10, s23, 5
	s_and_b32 s45, s10, 0x60
	s_mov_b64 s[10:11], 0x80
	s_lshl_b32 s5, s4, 8
	s_add_i32 m0, s18, 0x18000
	v_lshl_add_u64 v[6:7], v[6:7], 0, s[10:11]
	s_add_i32 s5, s5, 0
	s_lshl_b32 s33, s4, 13
	s_lshl_b32 s46, s45, 7
	s_waitcnt vmcnt(2)
	s_barrier
	global_load_lds_dwordx4 v[6:7], off
	v_lshl_add_u64 v[4:5], v[4:5], 0, s[10:11]
	s_add_i32 m0, s18, 0x1a000
	s_add_i32 s23, s18, 0x8000
	s_add_i32 s24, s18, 0xa000
	global_load_lds_dwordx4 v[4:5], off
	v_lshl_add_u64 v[2:3], v[2:3], 0, s[10:11]
	s_mov_b32 m0, s23
	s_add_u32 s26, s80, 0x40080
	global_load_lds_dwordx4 v[2:3], off
	v_lshl_add_u64 v[0:1], v[0:1], 0, s[10:11]
	s_mov_b32 m0, s24
	s_addc_u32 s27, s81, 0
	global_load_lds_dwordx4 v[0:1], off
	s_add_i32 m0, s18, 0x1c000
	v_lshl_add_u64 v[0:1], s[26:27], 0, v[142:143]
	global_load_lds_dwordx4 v[0:1], off
	v_lshl_add_u64 v[0:1], s[26:27], 0, v[146:147]
	s_add_i32 m0, s18, 0x1e000
	v_lshlrev_b32_e32 v2, 6, v240
	global_load_lds_dwordx4 v[0:1], off
	v_bfe_u32 v1, v240, 4, 2
	v_lshlrev_b32_e32 v148, 4, v1
	s_movk_i32 s26, 0x3c0
	v_lshlrev_b32_e32 v3, 2, v240
	v_and_or_b32 v2, v2, s26, v148
	v_and_b32_e32 v3, 32, v3
	v_lshl_or_b32 v179, v1, 3, s45
	v_lshlrev_b32_e32 v1, 8, v240
	v_bitop3_b32 v177, s46, v2, v3 bitop3:0xf6
	v_and_b32_e32 v1, 0x38000, v1
	v_lshlrev_b32_e32 v2, 11, v14
	v_and_b32_e32 v0, 15, v240
	v_or3_b32 v1, v12, v1, v2
	v_lshlrev_b32_e32 v4, 2, v0
	s_add_i32 s5, s5, 0x20400
	v_add_u32_e32 v152, v1, v13
	v_lshlrev_b32_e32 v1, 4, v15
	v_lshl_or_b32 v176, s4, 6, v0
	v_lshl_or_b32 v0, v0, 6, v148
	v_and_b32_e32 v5, 32, v4
	s_waitcnt vmcnt(6)
	s_cmpk_lt_u32 s25, 0x100
	v_and_b32_e32 v1, 0x78000, v1
	s_sext_i32_i8 s58, s44
	v_mov_b32_e32 v149, 0
	v_bitop3_b32 v0, v0, s33, v5 bitop3:0xde
	s_cselect_b64 s[44:45], -1, 0
	v_or3_b32 v1, v12, v1, v2
	s_add_i32 s25, 0, 0x10000
	s_add_i32 s26, 0, 0x14000
	s_mov_b32 s59, 0
	v_lshl_add_u64 v[150:151], s[70:71], 0, v[148:149]
	v_add_u32_e32 v178, s5, v4
	v_or_b32_e32 v180, 0xfffff800, v179
	v_mov_b32_e32 v153, v149
	v_add_u32_e32 v154, v1, v13
	v_mov_b32_e32 v155, v149
	v_mov_b64_e32 v[156:157], 0x600
	v_mov_b64_e32 v[158:159], 0x5ff
	v_add_u32_e32 v181, s25, v177
	v_add_u32_e32 v182, s26, v177
	v_add_u32_e32 v183, 0, v0
	v_mov_b32_e32 v184, 0x358637bd
	s_mov_b32 s27, 0x40000
	s_mov_b32 s33, 0x48000
	s_mov_b32 s56, 0x50000
	s_barrier
	s_mov_b32 s101, 0
	s_branch .LBB0_1757

.LBB0_1759:
	s_ashr_i32 s49, s48, 31
	s_lshl_b64 s[50:51], s[48:49], 19
	s_add_u32 s50, s12, s50
	s_addc_u32 s51, s13, s51
	s_and_b64 s[52:53], s[4:5], exec
	s_cselect_b32 s49, s51, s79
	s_cselect_b32 s54, s50, s78
	s_ashr_i32 s47, s46, 31
	s_lshl_b64 s[52:53], s[46:47], 19
	s_add_u32 s52, s14, s52
	s_addc_u32 s53, s15, s53
	s_and_b64 s[66:67], s[4:5], exec
	s_cselect_b32 s47, s53, s81
	s_cselect_b32 s55, s52, s80
	s_add_u32 s78, s78, 0x40080
	s_addc_u32 s79, s79, 0
	s_add_u32 s66, s80, 0x100
	v_mov_b32_e32 v0, 0
	s_addc_u32 s67, s81, 0
	s_mov_b32 s68, -2
	s_waitcnt lgkmcnt(0)
	s_cmp_eq_u32 s101, 0
	s_cbranch_scc1 .Lpb_8
	s_barrier
	s_mov_b32 s101, 0
.Lpb_8:
.LBB0_1760:
	ds_read_b128 v[128:131], v181
	ds_read_b128 v[132:135], v181 offset:1024
	ds_read_b128 v[136:139], v181 offset:2048
	ds_read_b128 v[160:163], v181 offset:3072
	ds_read_b128 v[164:167], v182
	ds_read_b128 v[168:171], v182 offset:1024
	ds_read_b128 v[186:189], v182 offset:2048
	ds_read_b128 v[190:193], v182 offset:3072
	s_add_u32 s69, s78, 0xfffc0080
	s_addc_u32 s73, s79, -1
	s_cmp_eq_u32 s68, 12
	s_cselect_b32 s83, s49, s73
	s_cselect_b32 s82, s54, s69
	s_cselect_b32 s81, s47, s67
	s_cselect_b32 s80, s55, s66
	v_lshl_add_u64 v[172:173], s[78:79], 0, v[152:153]
	s_add_i32 m0, s18, 0xc000
	ds_read_b128 v[194:197], v183
	ds_read_b128 v[198:201], v183 offset:1024
	ds_read_b128 v[202:205], v183 offset:2048
	ds_read_b128 v[206:209], v183 offset:3072
	ds_read_b128 v[210:213], v183 offset:4096
	ds_read_b128 v[214:217], v183 offset:5120
	ds_read_b128 v[218:221], v183 offset:6144
	ds_read_b128 v[222:225], v183 offset:7168
	global_load_lds_dwordx4 v[172:173], off
	s_add_i32 m0, s18, 0xe000
	v_lshl_add_u64 v[172:173], s[78:79], 0, v[154:155]
	global_load_lds_dwordx4 v[172:173], off
	s_cmp_eq_u32 s68, -2
	s_waitcnt vmcnt(8) lgkmcnt(0)
	s_barrier
	s_setprio 1
	s_cbranch_scc1 .Lzv_8_0
	v_mfma_f32_16x16x32_bf16 v[124:127], v[128:131], v[194:197], v[124:127]
	v_mfma_f32_16x16x32_bf16 v[124:127], v[132:135], v[198:201], v[124:127]
	v_mfma_f32_16x16x32_bf16 v[120:123], v[136:139], v[194:197], v[120:123]
	v_mfma_f32_16x16x32_bf16 v[120:123], v[160:163], v[198:201], v[120:123]
	v_mfma_f32_16x16x32_bf16 v[108:111], v[128:131], v[202:205], v[108:111]
	v_mfma_f32_16x16x32_bf16 v[108:111], v[132:135], v[206:209], v[108:111]
	v_mfma_f32_16x16x32_bf16 v[104:107], v[136:139], v[202:205], v[104:107]
	v_mfma_f32_16x16x32_bf16 v[104:107], v[160:163], v[206:209], v[104:107]
	v_mfma_f32_16x16x32_bf16 v[92:95], v[128:131], v[210:213], v[92:95]
	v_mfma_f32_16x16x32_bf16 v[92:95], v[132:135], v[214:217], v[92:95]
	v_mfma_f32_16x16x32_bf16 v[88:91], v[136:139], v[210:213], v[88:91]
	v_mfma_f32_16x16x32_bf16 v[88:91], v[160:163], v[214:217], v[88:91]
	v_mfma_f32_16x16x32_bf16 v[76:79], v[128:131], v[218:221], v[76:79]
	v_mfma_f32_16x16x32_bf16 v[76:79], v[132:135], v[222:225], v[76:79]
	v_mfma_f32_16x16x32_bf16 v[72:75], v[136:139], v[218:221], v[72:75]
	v_mfma_f32_16x16x32_bf16 v[72:75], v[160:163], v[222:225], v[72:75]
	v_mfma_f32_16x16x32_bf16 v[116:119], v[164:167], v[194:197], v[116:119]
	v_mfma_f32_16x16x32_bf16 v[116:119], v[168:171], v[198:201], v[116:119]
	v_mfma_f32_16x16x32_bf16 v[112:115], v[186:189], v[194:197], v[112:115]
	v_mfma_f32_16x16x32_bf16 v[112:115], v[190:193], v[198:201], v[112:115]
	v_mfma_f32_16x16x32_bf16 v[100:103], v[164:167], v[202:205], v[100:103]
	v_mfma_f32_16x16x32_bf16 v[100:103], v[168:171], v[206:209], v[100:103]
	v_mfma_f32_16x16x32_bf16 v[96:99], v[186:189], v[202:205], v[96:99]
	v_mfma_f32_16x16x32_bf16 v[96:99], v[190:193], v[206:209], v[96:99]
	v_mfma_f32_16x16x32_bf16 v[84:87], v[164:167], v[210:213], v[84:87]
	v_mfma_f32_16x16x32_bf16 v[84:87], v[168:171], v[214:217], v[84:87]
	v_mfma_f32_16x16x32_bf16 v[80:83], v[186:189], v[210:213], v[80:83]
	v_mfma_f32_16x16x32_bf16 v[80:83], v[190:193], v[214:217], v[80:83]
	v_mfma_f32_16x16x32_bf16 v[68:71], v[164:167], v[218:221], v[68:71]
	v_mfma_f32_16x16x32_bf16 v[68:71], v[168:171], v[222:225], v[68:71]
	s_setprio 3
	s_barrier
	v_mfma_f32_16x16x32_bf16 v[64:67], v[186:189], v[218:221], v[64:67]
	v_mfma_f32_16x16x32_bf16 v[64:67], v[190:193], v[222:225], v[64:67]
	s_setprio 0

.LBB0_1772:
	s_andn2_b64 vcc, exec, s[8:9]
	s_cbranch_vccnz .LBB0_1755
	s_mov_b32 s101, 1
	s_branch .LBB0_1755

.LBB0_2027:
	s_mov_b64 s[46:47], 0x80
	s_and_b32 s20, s5, 3
	s_add_i32 m0, s16, 0x18000
	v_lshl_add_u64 v[6:7], v[6:7], 0, s[46:47]
	s_lshl_b32 s5, s4, 13
	s_lshl_b32 s24, s20, 12
	s_waitcnt vmcnt(2)
	s_barrier
	global_load_lds_dwordx4 v[6:7], off
	v_lshl_add_u64 v[4:5], v[4:5], 0, s[46:47]
	s_add_i32 m0, s16, 0x1a000
	s_add_i32 s21, s16, 0x8000
	s_add_i32 s22, s16, 0xa000
	global_load_lds_dwordx4 v[4:5], off
	v_lshl_add_u64 v[0:1], v[0:1], 0, s[46:47]
	s_mov_b32 m0, s21
	s_add_u32 s6, s78, 0x40080
	global_load_lds_dwordx4 v[0:1], off
	v_lshl_add_u64 v[0:1], v[2:3], 0, s[46:47]
	s_mov_b32 m0, s22
	s_addc_u32 s7, s79, 0
	global_load_lds_dwordx4 v[0:1], off
	s_add_i32 m0, s16, 0x1c000
	v_lshl_add_u64 v[0:1], s[6:7], 0, v[194:195]
	global_load_lds_dwordx4 v[0:1], off
	v_lshl_add_u64 v[0:1], s[6:7], 0, v[198:199]
	s_add_i32 m0, s16, 0x1e000
	v_lshlrev_b32_e32 v4, 2, v240
	global_load_lds_dwordx4 v[0:1], off
	v_bfe_u32 v0, v240, 4, 2
	v_and_b32_e32 v1, 15, v240
	v_lshlrev_b32_e32 v3, 4, v0
	v_lshl_or_b32 v242, s4, 6, v1
	v_lshl_or_b32 v1, v1, 6, v3
	v_and_b32_e32 v4, 32, v4
	v_lshlrev_b32_e32 v5, 6, v240
	s_movk_i32 s4, 0x3c0
	v_lshlrev_b32_e32 v2, 3, v0
	v_bitop3_b32 v1, v1, s5, v4 bitop3:0xde
	v_and_or_b32 v3, v5, s4, v3
	v_cmp_eq_u32_e64 s[4:5], 0, v0
	v_lshlrev_b32_e32 v0, 8, v240
	v_lshl_or_b32 v244, s20, 5, v2
	v_and_b32_e32 v0, 0x38000, v0
	v_lshlrev_b32_e32 v2, 11, v10
	v_or3_b32 v0, v8, v0, v2
	v_add_u32_e32 v200, v0, v9
	v_lshlrev_b32_e32 v0, 4, v11
	v_and_b32_e32 v0, 0x78000, v0
	s_waitcnt vmcnt(6)
	s_cmpk_lt_u32 s23, 0x100
	v_or3_b32 v0, v8, v0, v2
	v_bitop3_b32 v243, s24, v3, v4 bitop3:0xf6
	s_cselect_b64 s[48:49], -1, 0
	v_add_u32_e32 v202, v0, v9
	s_add_i32 s26, 0, 0x10000
	s_add_i32 s27, 0, 0x14000
	v_mbcnt_lo_u32_b32 v0, -1, 0
	s_ashr_i32 s23, s34, 31
	s_mov_b32 s24, s34
	s_ashr_i32 s25, s2, 31
	v_mov_b32_e32 v201, v195
	v_mov_b32_e32 v203, v195
	v_add_u32_e32 v245, s26, v243
	v_add_u32_e32 v246, s27, v243
	v_add_u32_e32 v247, 0, v1
	v_mbcnt_hi_u32_b32 v248, -1, v0
	s_mov_b32 s33, 0
	s_barrier
	s_mov_b32 s101, 0
	s_branch .LBB0_2030

.LBB0_2036:
	s_ashr_i32 s53, s52, 31
	s_lshl_b64 s[54:55], s[52:53], 19
	s_add_u32 s58, s42, s54
	s_addc_u32 s59, s43, s55
	s_and_b64 s[54:55], s[6:7], exec
	s_cselect_b32 s53, s59, s77
	s_cselect_b32 s54, s58, s76
	s_ashr_i32 s51, s50, 31
	s_lshl_b64 s[56:57], s[50:51], 19
	s_add_u32 s72, s3, s56
	s_addc_u32 s73, s14, s57
	s_and_b64 s[56:57], s[6:7], exec
	s_cselect_b32 s51, s73, s79
	s_cselect_b32 s55, s72, s78
	s_add_u32 s76, s76, 0x40080
	s_addc_u32 s77, s77, 0
	s_add_u32 s56, s78, 0x100
	v_mov_b32_e32 v0, 0
	s_addc_u32 s57, s79, 0
	s_mov_b32 s66, -2
	s_cmp_eq_u32 s101, 0
	s_cbranch_scc1 .Lpb_9
	s_barrier
	s_mov_b32 s101, 0
.Lpb_9:
.LBB0_2037:
	ds_read_b128 v[120:123], v245
	ds_read_b128 v[124:127], v245 offset:1024
	ds_read_b128 v[128:131], v245 offset:2048
	ds_read_b128 v[132:135], v245 offset:3072
	ds_read_b128 v[144:147], v246
	ds_read_b128 v[148:151], v246 offset:1024
	ds_read_b128 v[152:155], v246 offset:2048
	ds_read_b128 v[156:159], v246 offset:3072
	s_add_u32 s67, s76, 0xfffc0080
	s_addc_u32 s68, s77, -1
	s_cmp_eq_u32 s66, 12
	s_cselect_b32 s81, s53, s68
	s_cselect_b32 s80, s54, s67
	s_cselect_b32 s79, s51, s57
	s_cselect_b32 s78, s55, s56
	v_lshl_add_u64 v[204:205], s[76:77], 0, v[200:201]
	s_add_i32 m0, s16, 0xc000
	ds_read_b128 v[160:163], v247
	ds_read_b128 v[164:167], v247 offset:1024
	ds_read_b128 v[168:171], v247 offset:2048
	ds_read_b128 v[172:175], v247 offset:3072
	ds_read_b128 v[176:179], v247 offset:4096
	ds_read_b128 v[180:183], v247 offset:5120
	ds_read_b128 v[184:187], v247 offset:6144
	ds_read_b128 v[188:191], v247 offset:7168
	global_load_lds_dwordx4 v[204:205], off
	s_add_i32 m0, s16, 0xe000
	v_lshl_add_u64 v[204:205], s[76:77], 0, v[202:203]
	global_load_lds_dwordx4 v[204:205], off
	s_cmp_eq_u32 s66, -2
	s_waitcnt vmcnt(8) lgkmcnt(0)
	s_barrier
	s_setprio 1
	s_cbranch_scc1 .Lzv_9_0
	v_mfma_f32_16x16x32_bf16 v[140:143], v[120:123], v[160:163], v[140:143]
	v_mfma_f32_16x16x32_bf16 v[140:143], v[124:127], v[164:167], v[140:143]
	v_mfma_f32_16x16x32_bf16 v[136:139], v[128:131], v[160:163], v[136:139]
	v_mfma_f32_16x16x32_bf16 v[136:139], v[132:135], v[164:167], v[136:139]
	v_mfma_f32_16x16x32_bf16 v[108:111], v[120:123], v[168:171], v[108:111]
	v_mfma_f32_16x16x32_bf16 v[108:111], v[124:127], v[172:175], v[108:111]
	v_mfma_f32_16x16x32_bf16 v[104:107], v[128:131], v[168:171], v[104:107]
	v_mfma_f32_16x16x32_bf16 v[104:107], v[132:135], v[172:175], v[104:107]
	v_mfma_f32_16x16x32_bf16 v[92:95], v[120:123], v[176:179], v[92:95]
	v_mfma_f32_16x16x32_bf16 v[92:95], v[124:127], v[180:183], v[92:95]
	v_mfma_f32_16x16x32_bf16 v[88:91], v[128:131], v[176:179], v[88:91]
	v_mfma_f32_16x16x32_bf16 v[88:91], v[132:135], v[180:183], v[88:91]
	v_mfma_f32_16x16x32_bf16 v[76:79], v[120:123], v[184:187], v[76:79]
	v_mfma_f32_16x16x32_bf16 v[76:79], v[124:127], v[188:191], v[76:79]
	v_mfma_f32_16x16x32_bf16 v[72:75], v[128:131], v[184:187], v[72:75]
	v_mfma_f32_16x16x32_bf16 v[72:75], v[132:135], v[188:191], v[72:75]
	v_mfma_f32_16x16x32_bf16 v[116:119], v[144:147], v[160:163], v[116:119]
	v_mfma_f32_16x16x32_bf16 v[116:119], v[148:151], v[164:167], v[116:119]
	v_mfma_f32_16x16x32_bf16 v[112:115], v[152:155], v[160:163], v[112:115]
	v_mfma_f32_16x16x32_bf16 v[112:115], v[156:159], v[164:167], v[112:115]
	v_mfma_f32_16x16x32_bf16 v[100:103], v[144:147], v[168:171], v[100:103]
	v_mfma_f32_16x16x32_bf16 v[100:103], v[148:151], v[172:175], v[100:103]
	v_mfma_f32_16x16x32_bf16 v[96:99], v[152:155], v[168:171], v[96:99]
	v_mfma_f32_16x16x32_bf16 v[96:99], v[156:159], v[172:175], v[96:99]
	v_mfma_f32_16x16x32_bf16 v[84:87], v[144:147], v[176:179], v[84:87]
	v_mfma_f32_16x16x32_bf16 v[84:87], v[148:151], v[180:183], v[84:87]
	v_mfma_f32_16x16x32_bf16 v[80:83], v[152:155], v[176:179], v[80:83]
	v_mfma_f32_16x16x32_bf16 v[80:83], v[156:159], v[180:183], v[80:83]
	v_mfma_f32_16x16x32_bf16 v[68:71], v[144:147], v[184:187], v[68:71]
	v_mfma_f32_16x16x32_bf16 v[68:71], v[148:151], v[188:191], v[68:71]
	s_setprio 3
	s_barrier
	v_mfma_f32_16x16x32_bf16 v[64:67], v[152:155], v[184:187], v[64:67]
	v_mfma_f32_16x16x32_bf16 v[64:67], v[156:159], v[188:191], v[64:67]
	s_setprio 0

.LBB0_2186:
	s_lshl_b32 s10, s23, 5
	s_and_b32 s33, s10, 0x60
	s_mov_b64 s[10:11], 0x80
	s_add_i32 m0, s17, 0x18000
	v_lshl_add_u64 v[6:7], v[6:7], 0, s[10:11]
	s_lshl_b32 s5, s4, 13
	s_lshl_b32 s43, s33, 7
	s_waitcnt vmcnt(2)
	s_barrier
	global_load_lds_dwordx4 v[6:7], off
	v_lshl_add_u64 v[4:5], v[4:5], 0, s[10:11]
	s_add_i32 m0, s17, 0x1a000
	s_add_i32 s23, s17, 0x8000
	s_add_i32 s24, s17, 0xa000
	global_load_lds_dwordx4 v[4:5], off
	v_lshl_add_u64 v[2:3], v[2:3], 0, s[10:11]
	s_mov_b32 m0, s23
	s_add_u32 s26, s72, 0x40080
	global_load_lds_dwordx4 v[2:3], off
	v_lshl_add_u64 v[0:1], v[0:1], 0, s[10:11]
	s_mov_b32 m0, s24
	s_addc_u32 s27, s73, 0
	global_load_lds_dwordx4 v[0:1], off
	s_add_i32 m0, s17, 0x1c000
	v_lshl_add_u64 v[0:1], s[26:27], 0, v[132:133]
	global_load_lds_dwordx4 v[0:1], off
	v_lshl_add_u64 v[0:1], s[26:27], 0, v[128:129]
	s_add_i32 m0, s17, 0x1e000
	v_mov_b32_e32 v137, 0
	global_load_lds_dwordx4 v[0:1], off
	v_and_b32_e32 v0, 15, v240
	v_bfe_u32 v1, v240, 4, 2
	v_lshl_or_b32 v170, s4, 6, v0
	s_lshl_b32 s4, s4, 8
	v_lshlrev_b32_e32 v136, 4, v1
	s_add_i32 s4, s4, 0
	v_lshl_or_b32 v2, v0, 6, v136
	v_lshlrev_b32_e32 v0, 2, v0
	s_add_i32 s4, s4, 0x20400
	v_and_b32_e32 v3, 32, v0
	v_add_u32_e32 v172, s4, v0
	v_lshlrev_b32_e32 v0, 8, v240
	v_lshl_or_b32 v173, v1, 3, s33
	v_and_b32_e32 v0, 0x38000, v0
	v_lshlrev_b32_e32 v1, 11, v15
	v_bitop3_b32 v2, v2, s5, v3 bitop3:0xde
	v_lshlrev_b32_e32 v3, 6, v240
	s_movk_i32 s5, 0x3c0
	v_or3_b32 v0, v13, v0, v1
	v_and_or_b32 v3, v3, s5, v136
	v_lshlrev_b32_e32 v4, 2, v240
	v_lshl_add_u64 v[138:139], s[70:71], 0, v[136:137]
	v_add_u32_e32 v136, v0, v14
	v_lshlrev_b32_e32 v0, 4, v12
	v_and_b32_e32 v4, 32, v4
	s_waitcnt vmcnt(6)
	s_cmpk_lt_u32 s25, 0x100
	v_and_b32_e32 v0, 0x78000, v0
	s_sext_i32_i8 s56, s42
	v_bitop3_b32 v171, s43, v3, v4 bitop3:0xf6
	s_cselect_b64 s[42:43], -1, 0
	v_or3_b32 v0, v13, v0, v1
	s_add_i32 s26, 0, 0x10000
	s_add_i32 s27, 0, 0x14000
	s_mov_b32 s57, 0
	v_add_u32_e32 v140, v0, v14
	v_mov_b32_e32 v141, v137
	v_mov_b64_e32 v[142:143], 0xb00
	v_mov_b64_e32 v[144:145], 0xaff
	s_movk_i32 s25, 0x161
	v_add_u32_e32 v174, s26, v171
	v_add_u32_e32 v175, s27, v171
	v_add_u32_e32 v176, 0, v2
	s_movk_i32 s33, 0x2000
	v_mov_b32_e32 v177, 0x358637bd
	s_movk_i32 s54, 0x1600
	s_barrier
	s_mov_b32 s101, 0
	s_branch .LBB0_2189

.LBB0_2191:
	s_ashr_i32 s47, s46, 31
	s_lshl_b64 s[48:49], s[46:47], 19
	s_add_u32 s48, s12, s48
	s_addc_u32 s49, s13, s49
	s_and_b64 s[50:51], s[4:5], exec
	s_cselect_b32 s47, s49, s59
	s_cselect_b32 s53, s48, s58
	s_ashr_i32 s45, s44, 31
	s_lshl_b64 s[50:51], s[44:45], 19
	s_add_u32 s50, s14, s50
	s_addc_u32 s51, s15, s51
	s_and_b64 s[66:67], s[4:5], exec
	s_cselect_b32 s45, s51, s73
	s_cselect_b32 s66, s50, s72
	s_add_u32 s58, s58, 0x40080
	s_addc_u32 s59, s59, 0
	s_add_u32 s67, s72, 0x100
	v_mov_b32_e32 v0, 0
	s_addc_u32 s68, s73, 0
	s_mov_b32 s69, -2
	s_waitcnt lgkmcnt(0)
	s_cmp_eq_u32 s101, 0
	s_cbranch_scc1 .Lpb_10
	s_barrier
	s_mov_b32 s101, 0
.Lpb_10:
.LBB0_2192:
	ds_read_b128 v[146:149], v174
	ds_read_b128 v[150:153], v174 offset:1024
	ds_read_b128 v[154:157], v174 offset:2048
	ds_read_b128 v[158:161], v174 offset:3072
	ds_read_b128 v[162:165], v175
	ds_read_b128 v[178:181], v175 offset:1024
	ds_read_b128 v[182:185], v175 offset:2048
	ds_read_b128 v[186:189], v175 offset:3072
	s_add_u32 s70, s58, 0xfffc0080
	s_addc_u32 s71, s59, -1
	s_cmp_eq_u32 s69, 12
	s_cselect_b32 s73, s47, s71
	s_cselect_b32 s72, s53, s70
	s_cselect_b32 s71, s45, s68
	s_cselect_b32 s70, s66, s67
	v_lshl_add_u64 v[166:167], s[58:59], 0, v[136:137]
	s_add_i32 m0, s17, 0xc000
	ds_read_b128 v[190:193], v176
	ds_read_b128 v[194:197], v176 offset:1024
	ds_read_b128 v[198:201], v176 offset:2048
	ds_read_b128 v[202:205], v176 offset:3072
	ds_read_b128 v[206:209], v176 offset:4096
	ds_read_b128 v[210:213], v176 offset:5120
	ds_read_b128 v[214:217], v176 offset:6144
	ds_read_b128 v[218:221], v176 offset:7168
	global_load_lds_dwordx4 v[166:167], off
	s_add_i32 m0, s17, 0xe000
	v_lshl_add_u64 v[166:167], s[58:59], 0, v[140:141]
	global_load_lds_dwordx4 v[166:167], off
	s_cmp_eq_u32 s69, -2
	s_waitcnt vmcnt(8) lgkmcnt(0)
	s_barrier
	s_setprio 1
	s_cbranch_scc1 .Lzv_10_0
	v_mfma_f32_16x16x32_bf16 v[124:127], v[146:149], v[190:193], v[124:127]
	v_mfma_f32_16x16x32_bf16 v[124:127], v[150:153], v[194:197], v[124:127]
	v_mfma_f32_16x16x32_bf16 v[116:119], v[154:157], v[190:193], v[116:119]
	v_mfma_f32_16x16x32_bf16 v[116:119], v[158:161], v[194:197], v[116:119]
	v_mfma_f32_16x16x32_bf16 v[108:111], v[146:149], v[198:201], v[108:111]
	v_mfma_f32_16x16x32_bf16 v[108:111], v[150:153], v[202:205], v[108:111]
	v_mfma_f32_16x16x32_bf16 v[100:103], v[154:157], v[198:201], v[100:103]
	v_mfma_f32_16x16x32_bf16 v[100:103], v[158:161], v[202:205], v[100:103]
	v_mfma_f32_16x16x32_bf16 v[92:95], v[146:149], v[206:209], v[92:95]
	v_mfma_f32_16x16x32_bf16 v[92:95], v[150:153], v[210:213], v[92:95]
	v_mfma_f32_16x16x32_bf16 v[84:87], v[154:157], v[206:209], v[84:87]
	v_mfma_f32_16x16x32_bf16 v[84:87], v[158:161], v[210:213], v[84:87]
	v_mfma_f32_16x16x32_bf16 v[76:79], v[146:149], v[214:217], v[76:79]
	v_mfma_f32_16x16x32_bf16 v[76:79], v[150:153], v[218:221], v[76:79]
	v_mfma_f32_16x16x32_bf16 v[68:71], v[154:157], v[214:217], v[68:71]
	v_mfma_f32_16x16x32_bf16 v[68:71], v[158:161], v[218:221], v[68:71]
	v_mfma_f32_16x16x32_bf16 v[120:123], v[162:165], v[190:193], v[120:123]
	v_mfma_f32_16x16x32_bf16 v[120:123], v[178:181], v[194:197], v[120:123]
	v_mfma_f32_16x16x32_bf16 v[112:115], v[182:185], v[190:193], v[112:115]
	v_mfma_f32_16x16x32_bf16 v[112:115], v[186:189], v[194:197], v[112:115]
	v_mfma_f32_16x16x32_bf16 v[104:107], v[162:165], v[198:201], v[104:107]
	v_mfma_f32_16x16x32_bf16 v[104:107], v[178:181], v[202:205], v[104:107]
	v_mfma_f32_16x16x32_bf16 v[96:99], v[182:185], v[198:201], v[96:99]
	v_mfma_f32_16x16x32_bf16 v[96:99], v[186:189], v[202:205], v[96:99]
	v_mfma_f32_16x16x32_bf16 v[88:91], v[162:165], v[206:209], v[88:91]
	v_mfma_f32_16x16x32_bf16 v[88:91], v[178:181], v[210:213], v[88:91]
	v_mfma_f32_16x16x32_bf16 v[80:83], v[182:185], v[206:209], v[80:83]
	v_mfma_f32_16x16x32_bf16 v[80:83], v[186:189], v[210:213], v[80:83]
	v_mfma_f32_16x16x32_bf16 v[72:75], v[162:165], v[214:217], v[72:75]
	v_mfma_f32_16x16x32_bf16 v[72:75], v[178:181], v[218:221], v[72:75]
	s_setprio 3
	s_barrier
	v_mfma_f32_16x16x32_bf16 v[64:67], v[182:185], v[214:217], v[64:67]
	v_mfma_f32_16x16x32_bf16 v[64:67], v[186:189], v[218:221], v[64:67]
	s_setprio 0

.LBB0_2199:
	s_waitcnt lgkmcnt(0)
	v_mul_f32_e32 v164, 0xbfb8aa3b, v166
	v_mul_f32_e32 v147, v166, v166
	v_pk_mul_f32 v[178:179], v[126:127], v[164:165] op_sel_hi:[1,0]
	v_pk_mul_f32 v[122:123], v[126:127], v[122:123]
	v_pk_mul_f32 v[126:127], v[116:117], v[164:165] op_sel_hi:[1,0]
	v_rcp_f32_e32 v166, v147
	v_pk_mul_f32 v[180:181], v[124:125], v[164:165] op_sel_hi:[1,0]
	v_exp_f32_e32 v126, v126
	v_exp_f32_e32 v127, v127
	v_exp_f32_e32 v180, v180
	v_exp_f32_e32 v178, v178
	v_exp_f32_e32 v179, v179
	v_exp_f32_e32 v181, v181
	v_pk_mul_f32 v[120:121], v[124:125], v[120:121]
	v_pk_mul_f32 v[124:125], v[118:119], v[164:165] op_sel_hi:[1,0]
	v_pk_fma_f32 v[126:127], v[126:127], v[166:167], v[166:167] op_sel_hi:[1,0,0]
	v_exp_f32_e32 v124, v124
	v_exp_f32_e32 v125, v125
	v_pk_fma_f32 v[178:179], v[178:179], v[166:167], v[166:167] op_sel_hi:[1,0,0]
	v_pk_fma_f32 v[180:181], v[180:181], v[166:167], v[166:167] op_sel_hi:[1,0,0]
	v_rcp_f32_e32 v126, v126
	v_rcp_f32_e32 v127, v127
	v_rcp_f32_e32 v180, v180
	v_rcp_f32_e32 v181, v181
	v_rcp_f32_e32 v178, v178
	v_rcp_f32_e32 v179, v179
	v_pk_fma_f32 v[124:125], v[124:125], v[166:167], v[166:167] op_sel_hi:[1,0,0]
	v_pk_mul_f32 v[112:113], v[116:117], v[112:113]
	v_rcp_f32_e32 v124, v124
	v_rcp_f32_e32 v125, v125
	v_pk_mul_f32 v[112:113], v[112:113], v[126:127]
	v_pk_mul_f32 v[122:123], v[122:123], v[178:179]
	v_pk_mul_f32 v[120:121], v[120:121], v[180:181]
	v_pk_mul_f32 v[114:115], v[118:119], v[114:115]
	v_cvt_pk_bf16_f32 v116, v120, v121
	v_cvt_pk_bf16_f32 v117, v122, v123
	v_cvt_pk_bf16_f32 v118, v112, v113
	v_mov_b64_e32 v[112:113], s[64:65]
	v_pk_mul_f32 v[114:115], v[114:115], v[124:125]
	v_mad_u64_u32 v[120:121], s[52:53], v160, s54, v[112:113]
	v_cvt_pk_bf16_f32 v119, v114, v115
	v_mov_b32_e32 v114, v121
	v_mul_f32_e32 v122, 0xbfb8aa3b, v167
	v_mul_f32_e32 v123, v167, v167
	v_mad_u64_u32 v[114:115], s[52:53], v161, s54, v[114:115]
	v_pk_mul_f32 v[126:127], v[110:111], v[122:123] op_sel_hi:[1,0]
	v_pk_mul_f32 v[160:161], v[108:109], v[122:123] op_sel_hi:[1,0]
	v_pk_mul_f32 v[106:107], v[110:111], v[106:107]
	v_pk_mul_f32 v[104:105], v[108:109], v[104:105]
	v_pk_mul_f32 v[108:109], v[102:103], v[122:123] op_sel_hi:[1,0]
	v_pk_mul_f32 v[110:111], v[100:101], v[122:123] op_sel_hi:[1,0]
	v_rcp_f32_e32 v124, v123
	v_exp_f32_e32 v110, v110
	v_exp_f32_e32 v108, v108
	v_exp_f32_e32 v109, v109
	v_exp_f32_e32 v111, v111
	v_lshl_or_b32 v182, s56, 7, v173
	v_exp_f32_e32 v160, v160
	v_exp_f32_e32 v126, v126
	v_exp_f32_e32 v127, v127
	v_exp_f32_e32 v161, v161
	v_ashrrev_i32_e32 v183, 31, v182
	v_mov_b32_e32 v121, v114
	v_lshlrev_b64 v[114:115], 1, v[182:183]
	v_lshl_add_u64 v[120:121], v[120:121], 0, v[114:115]
	v_pk_fma_f32 v[108:109], v[108:109], v[124:125], v[124:125] op_sel_hi:[1,0,0]
	v_pk_fma_f32 v[110:111], v[110:111], v[124:125], v[124:125] op_sel_hi:[1,0,0]
	global_store_dwordx4 v[120:121], v[116:119], off
	v_rcp_f32_e32 v110, v110
	v_rcp_f32_e32 v108, v108
	v_pk_fma_f32 v[116:117], v[126:127], v[124:125], v[124:125] op_sel_hi:[1,0,0]
	v_pk_fma_f32 v[118:119], v[160:161], v[124:125], v[124:125] op_sel_hi:[1,0,0]
	v_rcp_f32_e32 v109, v109
	v_rcp_f32_e32 v111, v111
	v_rcp_f32_e32 v118, v118
	v_rcp_f32_e32 v119, v119
	v_rcp_f32_e32 v116, v116
	v_rcp_f32_e32 v117, v117
	v_pk_mul_f32 v[98:99], v[102:103], v[98:99]
	v_pk_mul_f32 v[96:97], v[100:101], v[96:97]
	v_pk_mul_f32 v[100:101], v[98:99], v[108:109]
	v_pk_mul_f32 v[98:99], v[96:97], v[110:111]
	v_pk_mul_f32 v[106:107], v[106:107], v[116:117]
	v_pk_mul_f32 v[104:105], v[104:105], v[118:119]
	v_pk_mul_f32 v[90:91], v[94:95], v[90:91]
	v_cvt_pk_bf16_f32 v96, v104, v105
	v_cvt_pk_bf16_f32 v97, v106, v107
	v_cvt_pk_bf16_f32 v98, v98, v99
	v_cvt_pk_bf16_f32 v99, v100, v101
	v_mad_u64_u32 v[100:101], s[52:53], v156, s54, v[112:113]
	v_mul_f32_e32 v102, 0xbfb8aa3b, v162
	v_mul_f32_e32 v103, v162, v162
	v_pk_mul_f32 v[106:107], v[94:95], v[102:103] op_sel_hi:[1,0]
	v_pk_mul_f32 v[108:109], v[92:93], v[102:103] op_sel_hi:[1,0]
	v_pk_mul_f32 v[88:89], v[92:93], v[88:89]
	v_pk_mul_f32 v[92:93], v[86:87], v[102:103] op_sel_hi:[1,0]
	v_pk_mul_f32 v[94:95], v[84:85], v[102:103] op_sel_hi:[1,0]
	v_rcp_f32_e32 v104, v103
	v_exp_f32_e32 v94, v94
	v_exp_f32_e32 v92, v92
	v_exp_f32_e32 v93, v93
	v_exp_f32_e32 v95, v95
	v_exp_f32_e32 v108, v108
	v_exp_f32_e32 v106, v106
	v_exp_f32_e32 v107, v107
	v_exp_f32_e32 v109, v109
	v_lshl_add_u64 v[100:101], v[100:101], 0, v[114:115]
	v_pk_fma_f32 v[92:93], v[92:93], v[104:105], v[104:105] op_sel_hi:[1,0,0]
	v_pk_fma_f32 v[94:95], v[94:95], v[104:105], v[104:105] op_sel_hi:[1,0,0]
	global_store_dwordx4 v[100:101], v[96:99], off
	v_rcp_f32_e32 v94, v94
	v_rcp_f32_e32 v92, v92
	v_pk_fma_f32 v[96:97], v[106:107], v[104:105], v[104:105] op_sel_hi:[1,0,0]
	v_pk_fma_f32 v[98:99], v[108:109], v[104:105], v[104:105] op_sel_hi:[1,0,0]
	v_rcp_f32_e32 v93, v93
	v_rcp_f32_e32 v95, v95
	v_rcp_f32_e32 v98, v98
	v_rcp_f32_e32 v99, v99
	v_rcp_f32_e32 v96, v96
	v_rcp_f32_e32 v97, v97
	v_pk_mul_f32 v[82:83], v[86:87], v[82:83]
	v_pk_mul_f32 v[80:81], v[84:85], v[80:81]
	v_pk_mul_f32 v[84:85], v[82:83], v[92:93]
	v_pk_mul_f32 v[82:83], v[80:81], v[94:95]
	v_pk_mul_f32 v[90:91], v[90:91], v[96:97]
	v_pk_mul_f32 v[88:89], v[88:89], v[98:99]
	v_pk_mul_f32 v[74:75], v[78:79], v[74:75]
	v_cvt_pk_bf16_f32 v80, v88, v89
	v_cvt_pk_bf16_f32 v81, v90, v91
	v_cvt_pk_bf16_f32 v82, v82, v83
	v_cvt_pk_bf16_f32 v83, v84, v85
	v_mad_u64_u32 v[84:85], s[52:53], v152, s54, v[112:113]
	v_mul_f32_e32 v86, 0xbfb8aa3b, v163
	v_mul_f32_e32 v87, v163, v163
	v_pk_mul_f32 v[90:91], v[78:79], v[86:87] op_sel_hi:[1,0]
	v_pk_mul_f32 v[92:93], v[76:77], v[86:87] op_sel_hi:[1,0]
	v_pk_mul_f32 v[72:73], v[76:77], v[72:73]
	v_pk_mul_f32 v[76:77], v[70:71], v[86:87] op_sel_hi:[1,0]
	v_pk_mul_f32 v[78:79], v[68:69], v[86:87] op_sel_hi:[1,0]
	v_rcp_f32_e32 v88, v87
	v_exp_f32_e32 v78, v78
	v_exp_f32_e32 v76, v76
	v_exp_f32_e32 v77, v77
	v_exp_f32_e32 v79, v79
	v_exp_f32_e32 v92, v92
	v_exp_f32_e32 v90, v90
	v_exp_f32_e32 v91, v91
	v_exp_f32_e32 v93, v93
	v_lshl_add_u64 v[84:85], v[84:85], 0, v[114:115]
	v_pk_fma_f32 v[76:77], v[76:77], v[88:89], v[88:89] op_sel_hi:[1,0,0]
	v_pk_fma_f32 v[78:79], v[78:79], v[88:89], v[88:89] op_sel_hi:[1,0,0]
	global_store_dwordx4 v[84:85], v[80:83], off
	v_rcp_f32_e32 v78, v78
	v_rcp_f32_e32 v76, v76
	v_pk_fma_f32 v[80:81], v[90:91], v[88:89], v[88:89] op_sel_hi:[1,0,0]
	v_pk_fma_f32 v[82:83], v[92:93], v[88:89], v[88:89] op_sel_hi:[1,0,0]
	v_rcp_f32_e32 v77, v77
	v_rcp_f32_e32 v79, v79
	v_rcp_f32_e32 v82, v82
	v_rcp_f32_e32 v83, v83
	v_rcp_f32_e32 v80, v80
	v_rcp_f32_e32 v81, v81
	v_pk_mul_f32 v[66:67], v[70:71], v[66:67]
	v_pk_mul_f32 v[64:65], v[68:69], v[64:65]
	v_pk_mul_f32 v[68:69], v[66:67], v[76:77]
	v_pk_mul_f32 v[66:67], v[64:65], v[78:79]
	v_pk_mul_f32 v[74:75], v[74:75], v[80:81]
	v_pk_mul_f32 v[72:73], v[72:73], v[82:83]
	v_pk_mul_f32 v[58:59], v[62:63], v[58:59]
	v_cvt_pk_bf16_f32 v64, v72, v73
	v_cvt_pk_bf16_f32 v65, v74, v75
	v_cvt_pk_bf16_f32 v66, v66, v67
	v_cvt_pk_bf16_f32 v67, v68, v69
	v_mad_u64_u32 v[68:69], s[52:53], v150, s54, v[112:113]
	v_mul_f32_e32 v70, 0xbfb8aa3b, v154
	v_mul_f32_e32 v71, v154, v154
	v_pk_mul_f32 v[74:75], v[62:63], v[70:71] op_sel_hi:[1,0]
	v_pk_mul_f32 v[76:77], v[60:61], v[70:71] op_sel_hi:[1,0]
	v_pk_mul_f32 v[56:57], v[60:61], v[56:57]
	v_pk_mul_f32 v[60:61], v[54:55], v[70:71] op_sel_hi:[1,0]
	v_pk_mul_f32 v[62:63], v[52:53], v[70:71] op_sel_hi:[1,0]
	v_rcp_f32_e32 v72, v71
	v_exp_f32_e32 v62, v62
	v_exp_f32_e32 v60, v60
	v_exp_f32_e32 v61, v61
	v_exp_f32_e32 v63, v63
	v_exp_f32_e32 v76, v76
	v_exp_f32_e32 v74, v74
	v_exp_f32_e32 v75, v75
	v_exp_f32_e32 v77, v77
	v_lshl_add_u64 v[68:69], v[68:69], 0, v[114:115]
	v_pk_fma_f32 v[60:61], v[60:61], v[72:73], v[72:73] op_sel_hi:[1,0,0]
	v_pk_fma_f32 v[62:63], v[62:63], v[72:73], v[72:73] op_sel_hi:[1,0,0]
	global_store_dwordx4 v[68:69], v[64:67], off
	v_rcp_f32_e32 v62, v62
	v_rcp_f32_e32 v60, v60
	v_pk_fma_f32 v[64:65], v[74:75], v[72:73], v[72:73] op_sel_hi:[1,0,0]
	v_pk_fma_f32 v[66:67], v[76:77], v[72:73], v[72:73] op_sel_hi:[1,0,0]
	v_rcp_f32_e32 v61, v61
	v_rcp_f32_e32 v63, v63
	v_rcp_f32_e32 v66, v66
	v_rcp_f32_e32 v67, v67
	v_rcp_f32_e32 v64, v64
	v_rcp_f32_e32 v65, v65
	v_pk_mul_f32 v[50:51], v[54:55], v[50:51]
	v_pk_mul_f32 v[48:49], v[52:53], v[48:49]
	v_pk_mul_f32 v[52:53], v[50:51], v[60:61]
	v_pk_mul_f32 v[50:51], v[48:49], v[62:63]
	v_pk_mul_f32 v[58:59], v[58:59], v[64:65]
	v_pk_mul_f32 v[56:57], v[56:57], v[66:67]
	v_pk_mul_f32 v[42:43], v[46:47], v[42:43]
	v_cvt_pk_bf16_f32 v48, v56, v57
	v_cvt_pk_bf16_f32 v49, v58, v59
	v_cvt_pk_bf16_f32 v50, v50, v51
	v_cvt_pk_bf16_f32 v51, v52, v53
	v_mad_u64_u32 v[52:53], s[52:53], v158, s54, v[112:113]
	v_mov_b32_e32 v54, v53
	v_mad_u64_u32 v[54:55], s[52:53], v159, s54, v[54:55]
	v_mov_b32_e32 v53, v54
	v_mul_f32_e32 v54, 0xbfb8aa3b, v155
	v_mul_f32_e32 v55, v155, v155
	v_pk_mul_f32 v[58:59], v[46:47], v[54:55] op_sel_hi:[1,0]
	v_pk_mul_f32 v[60:61], v[44:45], v[54:55] op_sel_hi:[1,0]
	v_pk_mul_f32 v[40:41], v[44:45], v[40:41]
	v_pk_mul_f32 v[44:45], v[38:39], v[54:55] op_sel_hi:[1,0]
	v_pk_mul_f32 v[46:47], v[36:37], v[54:55] op_sel_hi:[1,0]
	v_rcp_f32_e32 v56, v55
	v_exp_f32_e32 v46, v46
	v_exp_f32_e32 v44, v44
	v_exp_f32_e32 v45, v45
	v_exp_f32_e32 v47, v47
	v_exp_f32_e32 v60, v60
	v_exp_f32_e32 v58, v58
	v_exp_f32_e32 v59, v59
	v_exp_f32_e32 v61, v61
	v_lshl_add_u64 v[52:53], v[52:53], 0, v[114:115]
	v_pk_fma_f32 v[44:45], v[44:45], v[56:57], v[56:57] op_sel_hi:[1,0,0]
	v_pk_fma_f32 v[46:47], v[46:47], v[56:57], v[56:57] op_sel_hi:[1,0,0]
	global_store_dwordx4 v[52:53], v[48:51], off
	v_rcp_f32_e32 v46, v46
	v_rcp_f32_e32 v44, v44
	v_pk_fma_f32 v[48:49], v[58:59], v[56:57], v[56:57] op_sel_hi:[1,0,0]
	v_pk_fma_f32 v[50:51], v[60:61], v[56:57], v[56:57] op_sel_hi:[1,0,0]
	v_rcp_f32_e32 v45, v45
	v_rcp_f32_e32 v47, v47
	v_rcp_f32_e32 v50, v50
	v_rcp_f32_e32 v51, v51
	v_rcp_f32_e32 v48, v48
	v_rcp_f32_e32 v49, v49
	v_pk_mul_f32 v[34:35], v[38:39], v[34:35]
	v_pk_mul_f32 v[32:33], v[36:37], v[32:33]
	v_pk_mul_f32 v[36:37], v[34:35], v[44:45]
	v_pk_mul_f32 v[34:35], v[32:33], v[46:47]
	v_add_u32_e32 v38, 16, v146
	v_pk_mul_f32 v[42:43], v[42:43], v[48:49]
	v_pk_mul_f32 v[40:41], v[40:41], v[50:51]
	v_mul_f32_e32 v39, v148, v148
	v_cvt_pk_bf16_f32 v32, v40, v41
	v_cvt_pk_bf16_f32 v33, v42, v43
	v_cvt_pk_bf16_f32 v34, v34, v35
	v_cvt_pk_bf16_f32 v35, v36, v37
	v_mad_i64_i32 v[36:37], s[52:53], v38, s54, v[112:113]
	v_mul_f32_e32 v38, 0xbfb8aa3b, v148
	v_pk_mul_f32 v[42:43], v[30:31], v[38:39] op_sel_hi:[1,0]
	v_pk_mul_f32 v[44:45], v[28:29], v[38:39] op_sel_hi:[1,0]
	v_pk_mul_f32 v[26:27], v[30:31], v[26:27]
	v_pk_mul_f32 v[24:25], v[28:29], v[24:25]
	v_pk_mul_f32 v[28:29], v[22:23], v[38:39] op_sel_hi:[1,0]
	v_pk_mul_f32 v[30:31], v[20:21], v[38:39] op_sel_hi:[1,0]
	v_rcp_f32_e32 v40, v39
	v_exp_f32_e32 v30, v30
	v_exp_f32_e32 v28, v28
	v_exp_f32_e32 v29, v29
	v_exp_f32_e32 v31, v31
	v_exp_f32_e32 v44, v44
	v_exp_f32_e32 v42, v42
	v_exp_f32_e32 v43, v43
	v_exp_f32_e32 v45, v45
	v_lshl_add_u64 v[36:37], v[36:37], 0, v[114:115]
	v_pk_fma_f32 v[28:29], v[28:29], v[40:41], v[40:41] op_sel_hi:[1,0,0]
	v_pk_fma_f32 v[30:31], v[30:31], v[40:41], v[40:41] op_sel_hi:[1,0,0]
	global_store_dwordx4 v[36:37], v[32:35], off
	v_rcp_f32_e32 v30, v30
	v_rcp_f32_e32 v28, v28
	v_pk_fma_f32 v[32:33], v[42:43], v[40:41], v[40:41] op_sel_hi:[1,0,0]
	v_pk_fma_f32 v[34:35], v[44:45], v[40:41], v[40:41] op_sel_hi:[1,0,0]
	v_rcp_f32_e32 v29, v29
	v_rcp_f32_e32 v31, v31
	v_rcp_f32_e32 v34, v34
	v_rcp_f32_e32 v35, v35
	v_rcp_f32_e32 v32, v32
	v_rcp_f32_e32 v33, v33
	v_pk_mul_f32 v[18:19], v[22:23], v[18:19]
	v_pk_mul_f32 v[16:17], v[20:21], v[16:17]
	v_pk_mul_f32 v[20:21], v[18:19], v[28:29]
	v_pk_mul_f32 v[18:19], v[16:17], v[30:31]
	v_add_u32_e32 v22, 32, v146
	v_pk_mul_f32 v[26:27], v[26:27], v[32:33]
	v_pk_mul_f32 v[24:25], v[24:25], v[34:35]
	v_mul_f32_e32 v23, v149, v149
	v_cvt_pk_bf16_f32 v16, v24, v25
	v_cvt_pk_bf16_f32 v17, v26, v27
	v_cvt_pk_bf16_f32 v18, v18, v19
	v_cvt_pk_bf16_f32 v19, v20, v21
	v_mad_i64_i32 v[20:21], s[52:53], v22, s54, v[112:113]
	v_mul_f32_e32 v22, 0xbfb8aa3b, v149
	v_pk_mul_f32 v[26:27], v[14:15], v[22:23] op_sel_hi:[1,0]
	v_pk_mul_f32 v[28:29], v[12:13], v[22:23] op_sel_hi:[1,0]
	v_pk_mul_f32 v[10:11], v[14:15], v[10:11]
	v_pk_mul_f32 v[8:9], v[12:13], v[8:9]
	v_pk_mul_f32 v[12:13], v[6:7], v[22:23] op_sel_hi:[1,0]
	v_pk_mul_f32 v[14:15], v[4:5], v[22:23] op_sel_hi:[1,0]
	v_rcp_f32_e32 v24, v23
	v_exp_f32_e32 v14, v14
	v_exp_f32_e32 v12, v12
	v_exp_f32_e32 v13, v13
	v_exp_f32_e32 v15, v15
	v_exp_f32_e32 v28, v28
	v_exp_f32_e32 v26, v26
	v_exp_f32_e32 v27, v27
	v_exp_f32_e32 v29, v29
	v_lshl_add_u64 v[20:21], v[20:21], 0, v[114:115]
	v_pk_fma_f32 v[12:13], v[12:13], v[24:25], v[24:25] op_sel_hi:[1,0,0]
	v_pk_fma_f32 v[14:15], v[14:15], v[24:25], v[24:25] op_sel_hi:[1,0,0]
	global_store_dwordx4 v[20:21], v[16:19], off
	v_rcp_f32_e32 v14, v14
	v_rcp_f32_e32 v12, v12
	v_pk_fma_f32 v[16:17], v[26:27], v[24:25], v[24:25] op_sel_hi:[1,0,0]
	v_pk_fma_f32 v[18:19], v[28:29], v[24:25], v[24:25] op_sel_hi:[1,0,0]
	v_rcp_f32_e32 v13, v13
	v_rcp_f32_e32 v15, v15
	v_rcp_f32_e32 v18, v18
	v_rcp_f32_e32 v19, v19
	v_rcp_f32_e32 v16, v16
	v_rcp_f32_e32 v17, v17
	v_pk_mul_f32 v[2:3], v[6:7], v[2:3]
	v_pk_mul_f32 v[0:1], v[4:5], v[0:1]
	v_pk_mul_f32 v[4:5], v[2:3], v[12:13]
	v_pk_mul_f32 v[2:3], v[0:1], v[14:15]
	v_add_u32_e32 v6, 48, v146
	v_pk_mul_f32 v[10:11], v[10:11], v[16:17]
	v_pk_mul_f32 v[8:9], v[8:9], v[18:19]
	s_andn2_b64 vcc, exec, s[4:5]
	v_cvt_pk_bf16_f32 v0, v8, v9
	v_cvt_pk_bf16_f32 v1, v10, v11
	v_cvt_pk_bf16_f32 v2, v2, v3
	v_cvt_pk_bf16_f32 v3, v4, v5
	v_mad_i64_i32 v[4:5], s[52:53], v6, s54, v[112:113]
	v_lshl_add_u64 v[4:5], v[4:5], 0, v[114:115]
	s_mov_b64 s[4:5], -1
	global_store_dwordx4 v[4:5], v[0:3], off
	s_cbranch_vccnz .LBB0_2188
	s_andn2_b64 vcc, exec, s[8:9]
	s_cbranch_vccnz .LBB0_2187
	s_mov_b32 s101, 1
	s_branch .LBB0_2187

.LBB0_2327:
	s_lshl_b32 s5, s5, 5
	s_mov_b64 s[8:9], 0x80
	s_and_b32 s5, s5, 0x60
	s_add_i32 m0, s25, 0x18000
	v_lshl_add_u64 v[6:7], v[6:7], 0, s[8:9]
	s_lshl_b32 s14, s0, 13
	s_lshl_b32 s15, s5, 7
	s_waitcnt vmcnt(2)
	s_barrier
	global_load_lds_dwordx4 v[6:7], off
	v_lshl_add_u64 v[4:5], v[4:5], 0, s[8:9]
	s_add_i32 m0, s25, 0x1a000
	s_add_i32 s33, s25, 0x8000
	s_add_i32 s35, s25, 0xa000
	global_load_lds_dwordx4 v[4:5], off
	v_lshl_add_u64 v[0:1], v[0:1], 0, s[8:9]
	s_mov_b32 m0, s33
	s_add_u32 s10, s18, 0xb0080
	global_load_lds_dwordx4 v[0:1], off
	v_lshl_add_u64 v[0:1], v[2:3], 0, s[8:9]
	s_mov_b32 m0, s35
	s_addc_u32 s11, s19, 0
	global_load_lds_dwordx4 v[0:1], off
	s_add_i32 m0, s25, 0x1c000
	v_lshl_add_u64 v[0:1], s[10:11], 0, v[166:167]
	global_load_lds_dwordx4 v[0:1], off
	v_lshl_add_u64 v[0:1], s[10:11], 0, v[170:171]
	s_add_i32 m0, s25, 0x1e000
	v_lshlrev_b32_e32 v2, 2, v240
	global_load_lds_dwordx4 v[0:1], off
	v_and_b32_e32 v0, 15, v240
	v_lshl_or_b32 v194, s0, 6, v0
	v_lshlrev_b32_e32 v1, 1, v10
	v_lshlrev_b32_e32 v3, 6, v240
	s_movk_i32 s0, 0x3c0
	v_lshl_or_b32 v0, v0, 6, v1
	v_and_b32_e32 v2, 32, v2
	v_and_or_b32 v1, v3, s0, v1
	v_bitop3_b32 v195, s15, v1, v2 bitop3:0xf6
	s_waitcnt vmcnt(6)
	s_cmpk_lt_u32 s4, 0x100
	v_add_u16_e32 v1, v8, v9
	v_bitop3_b32 v0, v0, s14, v2 bitop3:0xde
	s_cselect_b64 s[10:11], -1, 0
	v_lshrrev_b16_e32 v1, 1, v1
	s_add_i32 s37, 0, 0x10000
	s_add_i32 s38, 0, 0x14000
	s_sext_i32_i8 s42, s1
	s_ashr_i32 s36, s34, 31
	v_or_b32_e32 v196, s5, v10
	v_add_lshl_u32 v172, v11, v1, 1
	v_mov_b32_e32 v173, v167
	v_add_lshl_u32 v174, v12, v1, 1
	v_mov_b32_e32 v175, v167
	v_mov_b64_e32 v[176:177], 0x200
	v_mov_b64_e32 v[178:179], 0x1ff
	v_add_u32_e32 v197, s37, v195
	v_add_u32_e32 v198, s38, v195
	v_add_u32_e32 v199, 0, v0
	s_barrier
	s_mov_b32 s101, 0
	s_branch .LBB0_2330

.LBB0_2340:
	s_add_u32 s16, s16, 0xb0080
	s_addc_u32 s17, s17, 0
	s_add_u32 s43, s18, 0x100
	v_mov_b32_e32 v0, 0
	s_addc_u32 s44, s19, 0
	s_mov_b32 s45, -2
	s_cmp_eq_u32 s101, 0
	s_cbranch_scc1 .Lpb_11
	s_barrier
	s_mov_b32 s101, 0
.Lpb_11:
.LBB0_2341:
	ds_read_b128 v[128:131], v197
	ds_read_b128 v[132:135], v197 offset:1024
	ds_read_b128 v[136:139], v197 offset:2048
	ds_read_b128 v[140:143], v197 offset:3072
	ds_read_b128 v[144:147], v198
	ds_read_b128 v[148:151], v198 offset:1024
	ds_read_b128 v[152:155], v198 offset:2048
	ds_read_b128 v[156:159], v198 offset:3072
	s_add_u32 s18, s16, 0xfff50080
	s_addc_u32 s19, s17, -1
	s_cmp_eq_u32 s45, 40
	s_cselect_b32 s21, s5, s19
	s_cselect_b32 s20, s4, s18
	s_cselect_b32 s19, s15, s44
	s_cselect_b32 s18, s14, s43
	v_lshl_add_u64 v[192:193], s[16:17], 0, v[172:173]
	s_add_i32 m0, s25, 0xc000
	ds_read_b128 v[160:163], v199
	ds_read_b128 v[180:183], v199 offset:1024
	ds_read_b128 v[184:187], v199 offset:2048
	ds_read_b128 v[188:191], v199 offset:3072
	ds_read_b128 v[200:203], v199 offset:4096
	ds_read_b128 v[204:207], v199 offset:5120
	ds_read_b128 v[208:211], v199 offset:6144
	ds_read_b128 v[212:215], v199 offset:7168
	global_load_lds_dwordx4 v[192:193], off
	s_add_i32 m0, s25, 0xe000
	v_lshl_add_u64 v[192:193], s[16:17], 0, v[174:175]
	global_load_lds_dwordx4 v[192:193], off
	s_cmp_eq_u32 s45, -2
	s_waitcnt vmcnt(8) lgkmcnt(0)
	s_barrier
	s_setprio 1
	s_cbranch_scc1 .Lzv_11_0
	v_mfma_f32_16x16x32_bf16 v[124:127], v[128:131], v[160:163], v[124:127]
	v_mfma_f32_16x16x32_bf16 v[124:127], v[132:135], v[180:183], v[124:127]
	v_mfma_f32_16x16x32_bf16 v[120:123], v[136:139], v[160:163], v[120:123]
	v_mfma_f32_16x16x32_bf16 v[120:123], v[140:143], v[180:183], v[120:123]
	v_mfma_f32_16x16x32_bf16 v[108:111], v[128:131], v[184:187], v[108:111]
	v_mfma_f32_16x16x32_bf16 v[108:111], v[132:135], v[188:191], v[108:111]
	v_mfma_f32_16x16x32_bf16 v[104:107], v[136:139], v[184:187], v[104:107]
	v_mfma_f32_16x16x32_bf16 v[104:107], v[140:143], v[188:191], v[104:107]
	v_mfma_f32_16x16x32_bf16 v[96:99], v[128:131], v[200:203], v[96:99]
	v_mfma_f32_16x16x32_bf16 v[96:99], v[132:135], v[204:207], v[96:99]
	v_mfma_f32_16x16x32_bf16 v[88:91], v[136:139], v[200:203], v[88:91]
	v_mfma_f32_16x16x32_bf16 v[88:91], v[140:143], v[204:207], v[88:91]
	v_mfma_f32_16x16x32_bf16 v[80:83], v[128:131], v[208:211], v[80:83]
	v_mfma_f32_16x16x32_bf16 v[80:83], v[132:135], v[212:215], v[80:83]
	v_mfma_f32_16x16x32_bf16 v[72:75], v[136:139], v[208:211], v[72:75]
	v_mfma_f32_16x16x32_bf16 v[72:75], v[140:143], v[212:215], v[72:75]
	v_mfma_f32_16x16x32_bf16 v[116:119], v[144:147], v[160:163], v[116:119]
	v_mfma_f32_16x16x32_bf16 v[116:119], v[148:151], v[180:183], v[116:119]
	v_mfma_f32_16x16x32_bf16 v[112:115], v[152:155], v[160:163], v[112:115]
	v_mfma_f32_16x16x32_bf16 v[112:115], v[156:159], v[180:183], v[112:115]
	v_mfma_f32_16x16x32_bf16 v[100:103], v[144:147], v[184:187], v[100:103]
	v_mfma_f32_16x16x32_bf16 v[100:103], v[148:151], v[188:191], v[100:103]
	v_mfma_f32_16x16x32_bf16 v[92:95], v[152:155], v[184:187], v[92:95]
	v_mfma_f32_16x16x32_bf16 v[92:95], v[156:159], v[188:191], v[92:95]
	v_mfma_f32_16x16x32_bf16 v[84:87], v[144:147], v[200:203], v[84:87]
	v_mfma_f32_16x16x32_bf16 v[84:87], v[148:151], v[204:207], v[84:87]
	v_mfma_f32_16x16x32_bf16 v[76:79], v[152:155], v[200:203], v[76:79]
	v_mfma_f32_16x16x32_bf16 v[76:79], v[156:159], v[204:207], v[76:79]
	v_mfma_f32_16x16x32_bf16 v[68:71], v[144:147], v[208:211], v[68:71]
	v_mfma_f32_16x16x32_bf16 v[68:71], v[148:151], v[212:215], v[68:71]
	s_setprio 3
	s_barrier
	v_mfma_f32_16x16x32_bf16 v[64:67], v[152:155], v[208:211], v[64:67]
	v_mfma_f32_16x16x32_bf16 v[64:67], v[156:159], v[212:215], v[64:67]
	s_setprio 0

.LBB0_2344:
	v_lshl_add_u32 v128, s41, 8, v194
	v_lshl_or_b32 v130, s42, 8, v196
	v_ashrrev_i32_e32 v131, 31, v130
	v_ashrrev_i32_e32 v129, 31, v128
	v_lshl_add_u64 v[132:133], v[130:131], 1, s[12:13]
	v_lshlrev_b64 v[134:135], 11, v[128:129]
	v_or_b32_e32 v228, 16, v128
	v_lshl_add_u64 v[134:135], v[132:133], 0, v[134:135]
	v_ashrrev_i32_e32 v229, 31, v228
	global_load_dwordx4 v[200:203], v[134:135], off
	global_load_dwordx4 v[204:207], v[134:135], off offset:256
	v_lshlrev_b64 v[134:135], 11, v[228:229]
	v_lshl_add_u64 v[134:135], v[132:133], 0, v[134:135]
	global_load_dwordx4 v[208:211], v[134:135], off
	v_or_b32_e32 v192, 32, v128
	v_ashrrev_i32_e32 v193, 31, v192
	global_load_dwordx4 v[212:215], v[134:135], off offset:256
	v_lshlrev_b64 v[182:183], 2, v[130:131]
	v_lshlrev_b64 v[130:131], 11, v[192:193]
	v_lshl_add_u64 v[130:131], v[132:133], 0, v[130:131]
	global_load_dwordx4 v[216:219], v[130:131], off
	v_or_b32_e32 v190, 48, v128
	v_add_u32_e32 v188, 0x80, v128
	v_add_u32_e32 v186, 0x90, v128
	v_add_u32_e32 v184, 0xa0, v128
	v_add_u32_e32 v180, 0xb0, v128
	v_ashrrev_i32_e32 v191, 31, v190
	v_ashrrev_i32_e32 v189, 31, v188
	v_ashrrev_i32_e32 v187, 31, v186
	v_ashrrev_i32_e32 v185, 31, v184
	v_ashrrev_i32_e32 v181, 31, v180
	v_lshlrev_b64 v[128:129], 12, v[128:129]
	v_lshlrev_b64 v[134:135], 11, v[190:191]
	v_lshlrev_b64 v[136:137], 11, v[188:189]
	v_lshlrev_b64 v[138:139], 11, v[186:187]
	v_lshlrev_b64 v[140:141], 11, v[184:185]
	v_lshlrev_b64 v[142:143], 11, v[180:181]
	v_lshl_add_u64 v[128:129], s[62:63], 0, v[128:129]
	v_lshl_add_u64 v[134:135], v[132:133], 0, v[134:135]
	v_lshl_add_u64 v[136:137], v[132:133], 0, v[136:137]
	v_lshl_add_u64 v[138:139], v[132:133], 0, v[138:139]
	v_lshl_add_u64 v[230:231], v[132:133], 0, v[140:141]
	v_lshl_add_u64 v[232:233], v[132:133], 0, v[142:143]
	v_lshl_add_u64 v[234:235], v[128:129], 0, v[182:183]
	global_load_dwordx4 v[220:223], v[130:131], off offset:256
	global_load_dwordx4 v[224:227], v[134:135], off
	global_load_dwordx4 v[160:163], v[134:135], off offset:256
	global_load_dwordx4 v[156:159], v[136:137], off
	global_load_dwordx4 v[152:155], v[136:137], off offset:256
	global_load_dwordx4 v[148:151], v[138:139], off
	global_load_dwordx4 v[144:147], v[138:139], off offset:256
	global_load_dwordx4 v[140:143], v[230:231], off
	s_nop 0
	global_load_dwordx4 v[136:139], v[230:231], off offset:256
	global_load_dwordx4 v[132:135], v[232:233], off
	global_load_dwordx4 v[128:131], v[232:233], off offset:256
	s_and_b64 vcc, exec, s[0:1]
	s_mov_b64 s[0:1], -1
	s_waitcnt vmcnt(0)
	v_lshlrev_b32_e32 v230, 16, v200
	v_and_b32_e32 v231, 0xffff0000, v200
	v_lshlrev_b32_e32 v200, 16, v201
	v_and_b32_e32 v201, 0xffff0000, v201
	v_lshlrev_b32_e32 v238, 16, v206
	v_and_b32_e32 v239, 0xffff0000, v206
	v_lshlrev_b32_e32 v232, 16, v202
	v_and_b32_e32 v233, 0xffff0000, v202
	v_lshlrev_b32_e32 v202, 16, v203
	v_and_b32_e32 v203, 0xffff0000, v203
	v_lshlrev_b32_e32 v236, 16, v204
	v_and_b32_e32 v237, 0xffff0000, v204
	v_lshlrev_b32_e32 v204, 16, v205
	v_and_b32_e32 v205, 0xffff0000, v205
	v_lshlrev_b32_e32 v206, 16, v207
	v_and_b32_e32 v207, 0xffff0000, v207
	v_pk_fma_f32 v[126:127], v[126:127], 0.5, v[200:201] op_sel_hi:[1,0,1]
	v_pk_fma_f32 v[124:125], v[124:125], 0.5, v[230:231] op_sel_hi:[1,0,1]
	v_pk_fma_f32 v[112:113], v[112:113], 0.5, v[238:239] op_sel_hi:[1,0,1]
	v_pk_fma_f32 v[122:123], v[122:123], 0.5, v[202:203] op_sel_hi:[1,0,1]
	v_pk_fma_f32 v[120:121], v[120:121], 0.5, v[232:233] op_sel_hi:[1,0,1]
	v_pk_fma_f32 v[118:119], v[118:119], 0.5, v[204:205] op_sel_hi:[1,0,1]
	v_pk_fma_f32 v[116:117], v[116:117], 0.5, v[236:237] op_sel_hi:[1,0,1]
	v_pk_fma_f32 v[114:115], v[114:115], 0.5, v[206:207] op_sel_hi:[1,0,1]
	global_store_dwordx4 v[234:235], v[124:127], off nt
	global_store_dwordx4 v[234:235], v[120:123], off offset:16 nt
	global_store_dwordx4 v[234:235], v[116:119], off offset:512 nt
	global_store_dwordx4 v[234:235], v[112:115], off offset:528 nt
	v_lshlrev_b32_e32 v200, 16, v208
	v_and_b32_e32 v201, 0xffff0000, v208
	v_lshlrev_b32_e32 v112, 16, v210
	v_and_b32_e32 v113, 0xffff0000, v210
	v_pk_fma_f32 v[104:105], v[104:105], 0.5, v[112:113] op_sel_hi:[1,0,1]
	v_lshlrev_b64 v[112:113], 12, v[228:229]
	v_lshlrev_b32_e32 v202, 16, v209
	v_and_b32_e32 v203, 0xffff0000, v209
	v_lshlrev_b32_e32 v114, 16, v211
	v_and_b32_e32 v115, 0xffff0000, v211
	v_lshl_add_u64 v[112:113], s[62:63], 0, v[112:113]
	v_pk_fma_f32 v[110:111], v[110:111], 0.5, v[202:203] op_sel_hi:[1,0,1]
	v_pk_fma_f32 v[108:109], v[108:109], 0.5, v[200:201] op_sel_hi:[1,0,1]
	v_pk_fma_f32 v[106:107], v[106:107], 0.5, v[114:115] op_sel_hi:[1,0,1]
	v_lshl_add_u64 v[112:113], v[112:113], 0, v[182:183]
	global_store_dwordx4 v[112:113], v[108:111], off nt
	global_store_dwordx4 v[112:113], v[104:107], off offset:16 nt
	s_nop 0
	v_lshlrev_b32_e32 v108, 16, v214
	v_lshlrev_b32_e32 v104, 16, v212
	v_and_b32_e32 v105, 0xffff0000, v212
	v_lshlrev_b32_e32 v106, 16, v213
	v_and_b32_e32 v107, 0xffff0000, v213
	v_and_b32_e32 v109, 0xffff0000, v214
	v_lshlrev_b32_e32 v110, 16, v215
	v_and_b32_e32 v111, 0xffff0000, v215
	v_pk_fma_f32 v[102:103], v[102:103], 0.5, v[106:107] op_sel_hi:[1,0,1]
	v_pk_fma_f32 v[100:101], v[100:101], 0.5, v[104:105] op_sel_hi:[1,0,1]
	v_pk_fma_f32 v[92:93], v[92:93], 0.5, v[108:109] op_sel_hi:[1,0,1]
	v_pk_fma_f32 v[94:95], v[94:95], 0.5, v[110:111] op_sel_hi:[1,0,1]
	global_store_dwordx4 v[112:113], v[100:103], off offset:512 nt
	global_store_dwordx4 v[112:113], v[92:95], off offset:528 nt
	s_nop 0
	v_lshlrev_b32_e32 v100, 16, v218
	v_lshlrev_b32_e32 v92, 16, v216
	v_and_b32_e32 v93, 0xffff0000, v216
	v_pk_fma_f32 v[92:93], v[96:97], 0.5, v[92:93] op_sel_hi:[1,0,1]
	v_lshlrev_b64 v[96:97], 12, v[192:193]
	v_lshlrev_b32_e32 v94, 16, v217
	v_and_b32_e32 v95, 0xffff0000, v217
	v_and_b32_e32 v101, 0xffff0000, v218
	v_lshlrev_b32_e32 v102, 16, v219
	v_and_b32_e32 v103, 0xffff0000, v219
	v_lshl_add_u64 v[96:97], s[62:63], 0, v[96:97]
	v_pk_fma_f32 v[94:95], v[98:99], 0.5, v[94:95] op_sel_hi:[1,0,1]
	v_pk_fma_f32 v[90:91], v[90:91], 0.5, v[102:103] op_sel_hi:[1,0,1]
	v_pk_fma_f32 v[88:89], v[88:89], 0.5, v[100:101] op_sel_hi:[1,0,1]
	v_lshl_add_u64 v[96:97], v[96:97], 0, v[182:183]
	global_store_dwordx4 v[96:97], v[92:95], off nt
	global_store_dwordx4 v[96:97], v[88:91], off offset:16 nt
	s_nop 0
	v_lshlrev_b32_e32 v92, 16, v222
	v_lshlrev_b32_e32 v88, 16, v220
	v_and_b32_e32 v89, 0xffff0000, v220
	v_lshlrev_b32_e32 v90, 16, v221
	v_and_b32_e32 v91, 0xffff0000, v221
	v_and_b32_e32 v93, 0xffff0000, v222
	v_lshlrev_b32_e32 v94, 16, v223
	v_and_b32_e32 v95, 0xffff0000, v223
	v_pk_fma_f32 v[86:87], v[86:87], 0.5, v[90:91] op_sel_hi:[1,0,1]
	v_pk_fma_f32 v[84:85], v[84:85], 0.5, v[88:89] op_sel_hi:[1,0,1]
	v_pk_fma_f32 v[76:77], v[76:77], 0.5, v[92:93] op_sel_hi:[1,0,1]
	v_pk_fma_f32 v[78:79], v[78:79], 0.5, v[94:95] op_sel_hi:[1,0,1]
	global_store_dwordx4 v[96:97], v[84:87], off offset:512 nt
	global_store_dwordx4 v[96:97], v[76:79], off offset:528 nt
	s_nop 0
	v_lshlrev_b32_e32 v84, 16, v226
	v_lshlrev_b32_e32 v76, 16, v224
	v_and_b32_e32 v77, 0xffff0000, v224
	v_pk_fma_f32 v[76:77], v[80:81], 0.5, v[76:77] op_sel_hi:[1,0,1]
	v_lshlrev_b64 v[80:81], 12, v[190:191]
	v_lshlrev_b32_e32 v78, 16, v225
	v_and_b32_e32 v79, 0xffff0000, v225
	v_and_b32_e32 v85, 0xffff0000, v226
	v_lshlrev_b32_e32 v86, 16, v227
	v_and_b32_e32 v87, 0xffff0000, v227
	v_lshl_add_u64 v[80:81], s[62:63], 0, v[80:81]
	v_pk_fma_f32 v[78:79], v[82:83], 0.5, v[78:79] op_sel_hi:[1,0,1]
	v_pk_fma_f32 v[74:75], v[74:75], 0.5, v[86:87] op_sel_hi:[1,0,1]
	v_pk_fma_f32 v[72:73], v[72:73], 0.5, v[84:85] op_sel_hi:[1,0,1]
	v_lshl_add_u64 v[80:81], v[80:81], 0, v[182:183]
	global_store_dwordx4 v[80:81], v[76:79], off nt
	global_store_dwordx4 v[80:81], v[72:75], off offset:16 nt
	s_nop 0
	v_lshlrev_b32_e32 v76, 16, v162
	v_lshlrev_b32_e32 v72, 16, v160
	v_and_b32_e32 v73, 0xffff0000, v160
	v_lshlrev_b32_e32 v74, 16, v161
	v_and_b32_e32 v75, 0xffff0000, v161
	v_and_b32_e32 v77, 0xffff0000, v162
	v_lshlrev_b32_e32 v78, 16, v163
	v_and_b32_e32 v79, 0xffff0000, v163
	v_pk_fma_f32 v[70:71], v[70:71], 0.5, v[74:75] op_sel_hi:[1,0,1]
	v_pk_fma_f32 v[68:69], v[68:69], 0.5, v[72:73] op_sel_hi:[1,0,1]
	v_pk_fma_f32 v[64:65], v[64:65], 0.5, v[76:77] op_sel_hi:[1,0,1]
	v_pk_fma_f32 v[66:67], v[66:67], 0.5, v[78:79] op_sel_hi:[1,0,1]
	global_store_dwordx4 v[80:81], v[68:71], off offset:512 nt
	global_store_dwordx4 v[80:81], v[64:67], off offset:528 nt
	s_nop 0
	v_lshlrev_b32_e32 v68, 16, v158
	v_lshlrev_b32_e32 v64, 16, v156
	v_and_b32_e32 v65, 0xffff0000, v156
	v_pk_fma_f32 v[60:61], v[60:61], 0.5, v[64:65] op_sel_hi:[1,0,1]
	v_lshlrev_b64 v[64:65], 12, v[188:189]
	v_lshlrev_b32_e32 v66, 16, v157
	v_and_b32_e32 v67, 0xffff0000, v157
	v_and_b32_e32 v69, 0xffff0000, v158
	v_lshlrev_b32_e32 v70, 16, v159
	v_and_b32_e32 v71, 0xffff0000, v159
	v_lshl_add_u64 v[64:65], s[62:63], 0, v[64:65]
	v_pk_fma_f32 v[62:63], v[62:63], 0.5, v[66:67] op_sel_hi:[1,0,1]
	v_pk_fma_f32 v[58:59], v[58:59], 0.5, v[70:71] op_sel_hi:[1,0,1]
	v_pk_fma_f32 v[56:57], v[56:57], 0.5, v[68:69] op_sel_hi:[1,0,1]
	v_lshl_add_u64 v[64:65], v[64:65], 0, v[182:183]
	global_store_dwordx4 v[64:65], v[60:63], off nt
	global_store_dwordx4 v[64:65], v[56:59], off offset:16 nt
	s_nop 0
	v_lshlrev_b32_e32 v60, 16, v154
	v_lshlrev_b32_e32 v56, 16, v152
	v_and_b32_e32 v57, 0xffff0000, v152
	v_lshlrev_b32_e32 v58, 16, v153
	v_and_b32_e32 v59, 0xffff0000, v153
	v_and_b32_e32 v61, 0xffff0000, v154
	v_lshlrev_b32_e32 v62, 16, v155
	v_and_b32_e32 v63, 0xffff0000, v155
	v_pk_fma_f32 v[54:55], v[54:55], 0.5, v[58:59] op_sel_hi:[1,0,1]
	v_pk_fma_f32 v[52:53], v[52:53], 0.5, v[56:57] op_sel_hi:[1,0,1]
	v_pk_fma_f32 v[44:45], v[44:45], 0.5, v[60:61] op_sel_hi:[1,0,1]
	v_pk_fma_f32 v[46:47], v[46:47], 0.5, v[62:63] op_sel_hi:[1,0,1]
	global_store_dwordx4 v[64:65], v[52:55], off offset:512 nt
	global_store_dwordx4 v[64:65], v[44:47], off offset:528 nt
	s_nop 0
	v_lshlrev_b32_e32 v52, 16, v150
	v_lshlrev_b32_e32 v44, 16, v148
	v_and_b32_e32 v45, 0xffff0000, v148
	v_pk_fma_f32 v[44:45], v[48:49], 0.5, v[44:45] op_sel_hi:[1,0,1]
	v_lshlrev_b64 v[48:49], 12, v[186:187]
	v_lshlrev_b32_e32 v46, 16, v149
	v_and_b32_e32 v47, 0xffff0000, v149
	v_and_b32_e32 v53, 0xffff0000, v150
	v_lshlrev_b32_e32 v54, 16, v151
	v_and_b32_e32 v55, 0xffff0000, v151
	v_lshl_add_u64 v[48:49], s[62:63], 0, v[48:49]
	v_pk_fma_f32 v[46:47], v[50:51], 0.5, v[46:47] op_sel_hi:[1,0,1]
	v_pk_fma_f32 v[42:43], v[42:43], 0.5, v[54:55] op_sel_hi:[1,0,1]
	v_pk_fma_f32 v[40:41], v[40:41], 0.5, v[52:53] op_sel_hi:[1,0,1]
	v_lshl_add_u64 v[48:49], v[48:49], 0, v[182:183]
	global_store_dwordx4 v[48:49], v[44:47], off nt
	global_store_dwordx4 v[48:49], v[40:43], off offset:16 nt
	s_nop 0
	v_lshlrev_b32_e32 v44, 16, v146
	v_lshlrev_b32_e32 v40, 16, v144
	v_and_b32_e32 v41, 0xffff0000, v144
	v_lshlrev_b32_e32 v42, 16, v145
	v_and_b32_e32 v43, 0xffff0000, v145
	v_and_b32_e32 v45, 0xffff0000, v146
	v_lshlrev_b32_e32 v46, 16, v147
	v_and_b32_e32 v47, 0xffff0000, v147
	v_pk_fma_f32 v[38:39], v[38:39], 0.5, v[42:43] op_sel_hi:[1,0,1]
	v_pk_fma_f32 v[36:37], v[36:37], 0.5, v[40:41] op_sel_hi:[1,0,1]
	v_pk_fma_f32 v[28:29], v[28:29], 0.5, v[44:45] op_sel_hi:[1,0,1]
	v_pk_fma_f32 v[30:31], v[30:31], 0.5, v[46:47] op_sel_hi:[1,0,1]
	global_store_dwordx4 v[48:49], v[36:39], off offset:512 nt
	global_store_dwordx4 v[48:49], v[28:31], off offset:528 nt
	s_nop 0
	v_lshlrev_b32_e32 v36, 16, v142
	v_lshlrev_b32_e32 v28, 16, v140
	v_and_b32_e32 v29, 0xffff0000, v140
	v_pk_fma_f32 v[28:29], v[32:33], 0.5, v[28:29] op_sel_hi:[1,0,1]
	v_lshlrev_b64 v[32:33], 12, v[184:185]
	v_lshlrev_b32_e32 v30, 16, v141
	v_and_b32_e32 v31, 0xffff0000, v141
	v_and_b32_e32 v37, 0xffff0000, v142
	v_lshlrev_b32_e32 v38, 16, v143
	v_and_b32_e32 v39, 0xffff0000, v143
	v_lshl_add_u64 v[32:33], s[62:63], 0, v[32:33]
	v_pk_fma_f32 v[30:31], v[34:35], 0.5, v[30:31] op_sel_hi:[1,0,1]
	v_pk_fma_f32 v[26:27], v[26:27], 0.5, v[38:39] op_sel_hi:[1,0,1]
	v_pk_fma_f32 v[24:25], v[24:25], 0.5, v[36:37] op_sel_hi:[1,0,1]
	v_lshl_add_u64 v[32:33], v[32:33], 0, v[182:183]
	global_store_dwordx4 v[32:33], v[28:31], off nt
	global_store_dwordx4 v[32:33], v[24:27], off offset:16 nt
	s_nop 0
	v_lshlrev_b32_e32 v28, 16, v138
	v_lshlrev_b32_e32 v24, 16, v136
	v_and_b32_e32 v25, 0xffff0000, v136
	v_lshlrev_b32_e32 v26, 16, v137
	v_and_b32_e32 v27, 0xffff0000, v137
	v_and_b32_e32 v29, 0xffff0000, v138
	v_lshlrev_b32_e32 v30, 16, v139
	v_and_b32_e32 v31, 0xffff0000, v139
	v_pk_fma_f32 v[22:23], v[22:23], 0.5, v[26:27] op_sel_hi:[1,0,1]
	v_pk_fma_f32 v[20:21], v[20:21], 0.5, v[24:25] op_sel_hi:[1,0,1]
	v_pk_fma_f32 v[12:13], v[12:13], 0.5, v[28:29] op_sel_hi:[1,0,1]
	v_pk_fma_f32 v[14:15], v[14:15], 0.5, v[30:31] op_sel_hi:[1,0,1]
	global_store_dwordx4 v[32:33], v[20:23], off offset:512 nt
	global_store_dwordx4 v[32:33], v[12:15], off offset:528 nt
	s_nop 0
	v_lshlrev_b32_e32 v20, 16, v134
	v_lshlrev_b32_e32 v12, 16, v132
	v_and_b32_e32 v13, 0xffff0000, v132
	v_pk_fma_f32 v[12:13], v[16:17], 0.5, v[12:13] op_sel_hi:[1,0,1]
	v_lshlrev_b64 v[16:17], 12, v[180:181]
	v_lshlrev_b32_e32 v14, 16, v133
	v_and_b32_e32 v15, 0xffff0000, v133
	v_and_b32_e32 v21, 0xffff0000, v134
	v_lshlrev_b32_e32 v22, 16, v135
	v_and_b32_e32 v23, 0xffff0000, v135
	v_lshl_add_u64 v[16:17], s[62:63], 0, v[16:17]
	v_pk_fma_f32 v[14:15], v[18:19], 0.5, v[14:15] op_sel_hi:[1,0,1]
	v_pk_fma_f32 v[10:11], v[10:11], 0.5, v[22:23] op_sel_hi:[1,0,1]
	v_pk_fma_f32 v[8:9], v[8:9], 0.5, v[20:21] op_sel_hi:[1,0,1]
	v_lshl_add_u64 v[16:17], v[16:17], 0, v[182:183]
	global_store_dwordx4 v[16:17], v[12:15], off nt
	global_store_dwordx4 v[16:17], v[8:11], off offset:16 nt
	s_nop 0
	v_lshlrev_b32_e32 v12, 16, v130
	v_lshlrev_b32_e32 v8, 16, v128
	v_and_b32_e32 v9, 0xffff0000, v128
	v_lshlrev_b32_e32 v10, 16, v129
	v_and_b32_e32 v11, 0xffff0000, v129
	v_and_b32_e32 v13, 0xffff0000, v130
	v_lshlrev_b32_e32 v14, 16, v131
	v_and_b32_e32 v15, 0xffff0000, v131
	v_pk_fma_f32 v[6:7], v[6:7], 0.5, v[10:11] op_sel_hi:[1,0,1]
	v_pk_fma_f32 v[4:5], v[4:5], 0.5, v[8:9] op_sel_hi:[1,0,1]
	v_pk_fma_f32 v[2:3], v[2:3], 0.5, v[14:15] op_sel_hi:[1,0,1]
	v_pk_fma_f32 v[0:1], v[0:1], 0.5, v[12:13] op_sel_hi:[1,0,1]
	global_store_dwordx4 v[16:17], v[4:7], off offset:512 nt
	global_store_dwordx4 v[16:17], v[0:3], off offset:528 nt
	s_cbranch_vccnz .LBB0_2329
	s_andn2_b64 vcc, exec, s[6:7]
	s_cbranch_vccnz .LBB0_2328
	s_mov_b32 s101, 1
	s_branch .LBB0_2328
